# v31 + attention: raised wave priority during the VALU softmax sections (finishSM / max), normal priority during the QK and PV MFMA blocks
# speedup vs baseline: 1.0084x; 1.0084x over previous
; #define SBAR() __builtin_amdgcn_sched_barrier(0)
; #define ISSUE_K(j, stg) do { const long _k0 = TROW(j); const char* _kt = (const char*)Kh + _k0 * (LDK * 2); _Pragma("unroll") for (int _i = 0; _i < 3; ++_i) \
;     __builtin_amdgcn_global_load_lds((const unsigned*)(_kt + okk[_i]), (LAS unsigned*)(ldsL + A2_K + (stg) * SHM_K + (wid * 3 + _i) * 1024), 16, 0, 0); } while (0)
; #define ISSUE_V(j, stg) do { const long _k0 = TROW(j); const char* _vt = (const char*)Vh + _k0 * (LDV * 2); _Pragma("unroll") for (int _i = 0; _i < 2; ++_i) \
;     __builtin_amdgcn_global_load_lds((const unsigned*)(_vt + ovv[_i]), (LAS unsigned*)(ldsL + (stg) * SHM_V + (wid * 2 + _i) * 1024), 16, 0, 0); } while (0)
; __device__ __forceinline__ void qkt(f32x16& p0, f32x16& p1, const char* Ks, const bf16x8* qr, const char* qx, int r32, int hi, int mode) {
;   p0 = f32x16{}; p1 = f32x16{};
; #pragma unroll
;   for (int d0 = 0; d0 < 12; ++d0) { const int cb = (d0 * 16 + hi * 8) * 2;
;     bf16x8 b0 = *reinterpret_cast<const bf16x8*>(Ks + KSWZ(r32, cb));
;     bf16x8 b1 = *reinterpret_cast<const bf16x8*>(Ks + KSWZ(32 + r32, cb));
;     const bf16x8 qf = d0 < 8 ? qr[d0 < 8 ? d0 : 0] : *reinterpret_cast<const bf16x8*>(qx + (d0 - 8) * 1024);
;     p0 = __builtin_amdgcn_mfma_f32_32x32x16_bf16(b0, qf, p0, 0, 0, 0);
;     p1 = __builtin_amdgcn_mfma_f32_32x32x16_bf16(b1, qf, p1, 0, 0, 0); }
; __device__ __forceinline__ void attn_body2(const bf16_t* __restrict__ Qb, const bf16_t* __restrict__ Kh, const bf16_t* __restrict__ Vh, ...
;     ...
;   for (int j = 1; j + 1 < NT; j += 2) {
;     ISSUE_K(j + 1, 0); ISSUE_V(j, 1);
;     SBAR(); qkt(pB0, pB1, K_lds + SHM_K, qr, qx, r32, hi, 0);
.LBB0_317:
	s_cmp_lt_u32 s12, s84
	s_cselect_b32 s38, 0, s84
	s_cselect_b32 s39, s2, s83
	s_lshl_b32 s38, s38, 6
	s_sub_i32 s38, s39, s38
	s_add_i32 s58, s52, s38
	s_mul_i32 s38, s58, 0xc00
	s_mul_hi_i32 s39, s58, 0xc00
	s_add_u32 s38, s30, s38
	s_addc_u32 s39, s31, s39
	s_mov_b32 m0, s95
	v_lshl_add_u64 v[64:65], s[38:39], 0, v[132:133]
	s_add_i32 s63, s12, -1
	global_load_lds_dwordx4 v[64:65], off
	v_lshl_add_u64 v[64:65], s[38:39], 0, v[130:131]
	s_mov_b32 m0, s96
	s_cmp_lt_u32 s63, s84
	global_load_lds_dwordx4 v[64:65], off
	v_lshl_add_u64 v[64:65], s[38:39], 0, v[136:137]
	s_cselect_b32 s38, 0, s84
	s_cselect_b32 s39, s2, s83
	s_lshl_b32 s38, s38, 6
	s_sub_i32 s38, s39, s38
	s_add_i32 s38, s52, s38
	s_sub_i32 s38, s38, 64
	s_ashr_i32 s39, s38, 31
	s_mov_b32 m0, s97
	s_lshl_b64 s[38:39], s[38:39], 11
	s_add_i32 s62, s3, 0x4000
	global_load_lds_dwordx4 v[64:65], off
	v_lshl_add_u64 v[64:65], v[140:141], 0, s[38:39]
	s_mov_b32 m0, s62
	s_add_i32 s56, s3, 0x4400
	global_load_lds_dwordx4 v[64:65], off
	v_lshl_add_u64 v[64:65], v[64:65], 0, s[22:23]
	s_mov_b32 m0, s56
	s_nop 0
	global_load_lds_dwordx4 v[64:65], off
	s_setprio 0
	ds_read_b128 v[64:67], v174 offset:49152
	ds_read_b128 v[68:71], v174 offset:61440
	ds_read_b128 v[208:211], v166 offset:49152
	ds_read_b128 v[212:215], v166 offset:61440
	ds_read_b128 v[176:179], v162 offset:49152
	ds_read_b128 v[180:183], v162 offset:61440
	v_exp_f32_e32 v156, v156
	v_exp_f32_e32 v157, v157
	s_waitcnt lgkmcnt(4)
	v_mfma_f32_32x32x16_bf16 v[80:95], v[64:67], v[96:99], 0
	v_exp_f32_e32 v154, v154
	v_exp_f32_e32 v155, v155
	v_exp_f32_e32 v152, v152
	v_exp_f32_e32 v153, v153
	v_exp_f32_e32 v190, v150
	v_exp_f32_e32 v207, v151
	v_cvt_pk_bf16_f32 v150, v156, v157
	v_mfma_f32_32x32x16_bf16 v[64:79], v[68:71], v[96:99], 0
	v_cvt_pk_bf16_f32 v151, v154, v155
	s_waitcnt lgkmcnt(2)
	v_mfma_f32_32x32x16_bf16 v[64:79], v[212:215], v[100:103], v[64:79]
	v_mfma_f32_32x32x16_bf16 v[80:95], v[208:211], v[100:103], v[80:95]
	ds_read_b128 v[208:211], v163 offset:49152
	ds_read_b128 v[212:215], v163 offset:61440
	s_waitcnt lgkmcnt(2)
	v_mfma_f32_32x32x16_bf16 v[64:79], v[180:183], v[104:107], v[64:79]
	v_mfma_f32_32x32x16_bf16 v[80:95], v[176:179], v[104:107], v[80:95]
	ds_read_b128 v[176:179], v164 offset:49152
	ds_read_b128 v[180:183], v164 offset:61440
	s_waitcnt lgkmcnt(2)
	v_mfma_f32_32x32x16_bf16 v[64:79], v[212:215], v[108:111], v[64:79]
	v_mfma_f32_32x32x16_bf16 v[80:95], v[208:211], v[108:111], v[80:95]
	ds_read_b128 v[208:211], v165 offset:49152
	ds_read_b128 v[212:215], v165 offset:61440
	s_waitcnt lgkmcnt(2)
	v_mfma_f32_32x32x16_bf16 v[64:79], v[180:183], v[112:115], v[64:79]
	v_mfma_f32_32x32x16_bf16 v[80:95], v[176:179], v[112:115], v[80:95]
	ds_read_b128 v[176:179], v167 offset:49152
	ds_read_b128 v[180:183], v167 offset:61440
	s_waitcnt lgkmcnt(2)
	v_mfma_f32_32x32x16_bf16 v[64:79], v[212:215], v[116:119], v[64:79]
	v_mfma_f32_32x32x16_bf16 v[80:95], v[208:211], v[116:119], v[80:95]
	ds_read_b128 v[208:211], v168 offset:49152
	ds_read_b128 v[212:215], v168 offset:61440
	s_waitcnt lgkmcnt(2)
	v_mfma_f32_32x32x16_bf16 v[64:79], v[180:183], v[120:123], v[64:79]
	v_mfma_f32_32x32x16_bf16 v[80:95], v[176:179], v[120:123], v[80:95]
	ds_read_b128 v[176:179], v169 offset:49152
	ds_read_b128 v[180:183], v169 offset:61440
	ds_read_b128 v[184:187], v173
	s_waitcnt lgkmcnt(3)
	v_mfma_f32_32x32x16_bf16 v[64:79], v[212:215], v[124:127], v[64:79]
	v_mfma_f32_32x32x16_bf16 v[80:95], v[208:211], v[124:127], v[80:95]
	ds_read_b128 v[208:211], v170 offset:49152
	ds_read_b128 v[212:215], v170 offset:61440
	ds_read_b128 v[216:219], v173 offset:1024
	s_waitcnt lgkmcnt(3)
	v_mfma_f32_32x32x16_bf16 v[64:79], v[180:183], v[184:187], v[64:79]
	v_mfma_f32_32x32x16_bf16 v[80:95], v[176:179], v[184:187], v[80:95]
	ds_read_b128 v[176:179], v171 offset:49152
	ds_read_b128 v[180:183], v171 offset:61440
	ds_read_b128 v[184:187], v173 offset:2048
	s_waitcnt lgkmcnt(3)
	v_mfma_f32_32x32x16_bf16 v[64:79], v[212:215], v[216:219], v[64:79]
	v_mfma_f32_32x32x16_bf16 v[80:95], v[208:211], v[216:219], v[80:95]
	ds_read_b128 v[208:211], v172 offset:49152
	ds_read_b128 v[212:215], v172 offset:61440
	ds_read_b128 v[216:219], v173 offset:3072
	s_waitcnt lgkmcnt(3)
	v_mfma_f32_32x32x16_bf16 v[64:79], v[180:183], v[184:187], v[64:79]
	v_mfma_f32_32x32x16_bf16 v[80:95], v[176:179], v[184:187], v[80:95]
	s_waitcnt lgkmcnt(0)
; __device__ __forceinline__ void finishSM(f32x16& p0, f32x16& p1, float alpha, float& l_reg, bf16x8& pa0, bf16x8& pa1, bf16x8& pa2, bf16x8& pa3) {
; #pragma unroll
;   for (int r = 0; r < 16; ++r) p1[r] = __builtin_amdgcn_exp2f(p1[r]);
;   float ps = 0;
; #pragma unroll
;   for (int r = 0; r < 16; ++r) ps += p0[r];
; #pragma unroll
;   for (int r = 0; r < 16; ++r) ps += p1[r];
;   { auto rr = __builtin_amdgcn_permlane32_swap(__float_as_uint(ps), __float_as_uint(ps), false, false);
;     ps = __uint_as_float(rr[0]) + __uint_as_float(rr[1]); }
;   l_reg = l_reg * alpha + ps;
;     ...
;   PK4(p0, 0, pa0); PK4(p0, 8, pa1); PK4(p1, 0, pa2); PK4(p1, 8, pa3);
;     ...
; }
; __device__ __forceinline__ void qkt(f32x16& p0, f32x16& p1, const char* Ks, const bf16x8* qr, const char* qx, int r32, int hi, int mode) {
;   p0 = f32x16{}; p1 = f32x16{};
; #pragma unroll
;   for (int d0 = 0; d0 < 12; ++d0) { const int cb = (d0 * 16 + hi * 8) * 2;
;     bf16x8 b0 = *reinterpret_cast<const bf16x8*>(Ks + KSWZ(r32, cb));
;     bf16x8 b1 = *reinterpret_cast<const bf16x8*>(Ks + KSWZ(32 + r32, cb));
;     const bf16x8 qf = d0 < 8 ? qr[d0 < 8 ? d0 : 0] : *reinterpret_cast<const bf16x8*>(qx + (d0 - 8) * 1024);
;     p0 = __builtin_amdgcn_mfma_f32_32x32x16_bf16(b0, qf, p0, 0, 0, 0);
;     p1 = __builtin_amdgcn_mfma_f32_32x32x16_bf16(b1, qf, p1, 0, 0, 0); }
;   if (mode != 0) {
;     constexpr float NEG = -1e30f;
; #pragma unroll
;     for (int r = 0; r < 16; ++r) p1[r] = NEG;
; #pragma unroll
;     for (int r = 8; r < 16; ++r) p0[r] = NEG;
;     if (mode == 2) {
; #pragma unroll
;       for (int r = 0; r < 8; ++r) p0[r] = NEG; }
;   }
; }
; __device__ __forceinline__ int v_st(int k, int c) { const int kk = (k & ~0xC) | ((k & 4) << 1) | ((k & 8) >> 1); return ((kk >> 3) * 4 + (c >> 5)) * 512 + ((kk & 7) * 32 + (c & 31)) * 2; }
; __device__ __forceinline__ int v_rd_base(int lane) { return ((lane & 3) << 3) | (((lane >> 2) & 3) << 6) | (((lane >> 4) & 1) << 5) | (((lane >> 5) & 1) << 8); }
; template <int OFF> __device__ __forceinline__ s16x4 tr_read(int vb) {
;   s16x4 r; asm volatile("ds_read_b64_tr_b16 %0, %1 offset:%2" : "=&v"(r) : "v"(vb), "i"(OFF) : "memory"); return r;
; }
; template <int D0> __device__ __forceinline__ void pv_one(f32x16& od, int vb, bf16x8 pa0, bf16x8 pa1, bf16x8 pa2, bf16x8 pa3) {
	v_mfma_f32_32x32x16_bf16 v[64:79], v[212:215], v[216:219], v[64:79]
	v_exp_f32_e32 v214, v142
	v_add_f32_e32 v142, 0, v199
	v_add_f32_e32 v142, v200, v142
	v_add_f32_e32 v142, v201, v142
	v_add_f32_e32 v142, v203, v142
	v_add_f32_e32 v142, v204, v142
	v_add_f32_e32 v142, v206, v142
	v_add_f32_e32 v142, v202, v142
	v_add_f32_e32 v142, v205, v142
	v_add_f32_e32 v142, v191, v142
	v_add_f32_e32 v142, v193, v142
	v_add_f32_e32 v142, v194, v142
	v_add_f32_e32 v142, v197, v142
	v_add_f32_e32 v142, v192, v142
	v_add_f32_e32 v142, v195, v142
	v_add_f32_e32 v142, v196, v142
	v_add_f32_e32 v142, v198, v142
	v_add_f32_e32 v142, v156, v142
	v_add_f32_e32 v142, v157, v142
	v_add_f32_e32 v142, v154, v142
	v_add_f32_e32 v142, v155, v142
	v_mfma_f32_32x32x16_bf16 v[80:95], v[208:211], v[216:219], v[80:95]
	s_setprio 1
	v_exp_f32_e32 v208, v148
	v_add_f32_e32 v142, v152, v142
	v_exp_f32_e32 v209, v149
	v_add_f32_e32 v142, v153, v142
	v_exp_f32_e32 v210, v146
	v_add_f32_e32 v142, v190, v142
	v_exp_f32_e32 v211, v147
	v_add_f32_e32 v142, v207, v142
	v_exp_f32_e32 v212, v144
	v_add_f32_e32 v142, v208, v142
	v_exp_f32_e32 v213, v145
	v_add_f32_e32 v142, v209, v142
	v_add_f32_e32 v142, v210, v142
	v_exp_f32_e32 v215, v143
	v_add_f32_e32 v142, v211, v142
	v_add_f32_e32 v142, v212, v142
	v_add_f32_e32 v142, v213, v142
	v_add_f32_e32 v142, v214, v142
	v_add_f32_e32 v188, v215, v142
	v_mov_b32_e32 v189, v188
	v_cvt_pk_bf16_f32 v142, v199, v200
	v_cvt_pk_bf16_f32 v144, v204, v206
	v_permlane32_swap_b32_e32 v188, v189
	v_cvt_pk_bf16_f32 v143, v201, v203
	v_cvt_pk_bf16_f32 v145, v202, v205
	v_permlane32_swap_b32_e32 v142, v144
	v_cvt_pk_bf16_f32 v146, v191, v193
	v_cvt_pk_bf16_f32 v147, v194, v197
	v_cvt_pk_bf16_f32 v148, v192, v195
	v_cvt_pk_bf16_f32 v149, v196, v198
	v_cvt_pk_bf16_f32 v152, v152, v153
	v_cvt_pk_bf16_f32 v153, v190, v207
	v_cvt_pk_bf16_f32 v154, v208, v209
	v_cvt_pk_bf16_f32 v155, v210, v211
	v_cvt_pk_bf16_f32 v156, v212, v213
	v_cvt_pk_bf16_f32 v157, v214, v215
	v_permlane32_swap_b32_e32 v143, v145
	v_permlane32_swap_b32_e32 v146, v148
	v_permlane32_swap_b32_e32 v147, v149
	v_permlane32_swap_b32_e32 v150, v152
	v_permlane32_swap_b32_e32 v151, v153
	v_permlane32_swap_b32_e32 v154, v156
	v_permlane32_swap_b32_e32 v155, v157
	s_setprio 0
	ds_read_b64_tr_b16 v[190:191], v161 offset:0
	ds_read_b64_tr_b16 v[192:193], v161 offset:0x800
	ds_read_b64_tr_b16 v[194:195], v161 offset:0x1000
	ds_read_b64_tr_b16 v[196:197], v161 offset:0x1800
	ds_read_b64_tr_b16 v[198:199], v161 offset:0x2000
	ds_read_b64_tr_b16 v[200:201], v161 offset:0x2800
	ds_read_b64_tr_b16 v[202:203], v161 offset:0x3000
	ds_read_b64_tr_b16 v[204:205], v161 offset:0x3800
	s_waitcnt lgkmcnt(6)
	s_nop 0
	v_mfma_f32_32x32x16_bf16 v[48:63], v[142:145], v[190:193], v[48:63]
	ds_read_b64_tr_b16 v[190:191], v161 offset:0x200
	ds_read_b64_tr_b16 v[192:193], v161 offset:0xa00
	s_waitcnt lgkmcnt(6)
	v_mfma_f32_32x32x16_bf16 v[48:63], v[146:149], v[194:197], v[48:63]
	ds_read_b64_tr_b16 v[194:195], v161 offset:0x1200
	ds_read_b64_tr_b16 v[196:197], v161 offset:0x1a00
	s_waitcnt lgkmcnt(6)
	v_mfma_f32_32x32x16_bf16 v[48:63], v[150:153], v[198:201], v[48:63]
	ds_read_b64_tr_b16 v[198:199], v161 offset:0x2200
	ds_read_b64_tr_b16 v[200:201], v161 offset:0x2a00
	s_waitcnt lgkmcnt(6)
	v_mfma_f32_32x32x16_bf16 v[48:63], v[154:157], v[202:205], v[48:63]
	ds_read_b64_tr_b16 v[202:203], v161 offset:0x3200
	ds_read_b64_tr_b16 v[204:205], v161 offset:0x3a00
	s_waitcnt lgkmcnt(6)
	v_mfma_f32_32x32x16_bf16 v[32:47], v[142:145], v[190:193], v[32:47]
	ds_read_b64_tr_b16 v[190:191], v161 offset:0x400
	ds_read_b64_tr_b16 v[192:193], v161 offset:0xc00
	s_waitcnt lgkmcnt(6)
	v_mfma_f32_32x32x16_bf16 v[32:47], v[146:149], v[194:197], v[32:47]
	ds_read_b64_tr_b16 v[194:195], v161 offset:0x1400
	ds_read_b64_tr_b16 v[196:197], v161 offset:0x1c00
	s_waitcnt lgkmcnt(6)
	v_mfma_f32_32x32x16_bf16 v[32:47], v[150:153], v[198:201], v[32:47]
	ds_read_b64_tr_b16 v[198:199], v161 offset:0x2400
	ds_read_b64_tr_b16 v[200:201], v161 offset:0x2c00
	s_waitcnt lgkmcnt(6)
	v_mfma_f32_32x32x16_bf16 v[32:47], v[154:157], v[202:205], v[32:47]
	ds_read_b64_tr_b16 v[202:203], v161 offset:0x3400
	ds_read_b64_tr_b16 v[204:205], v161 offset:0x3c00
	s_waitcnt lgkmcnt(6)
	v_mfma_f32_32x32x16_bf16 v[16:31], v[142:145], v[190:193], v[16:31]
	ds_read_b64_tr_b16 v[190:191], v161 offset:0x600
	ds_read_b64_tr_b16 v[192:193], v161 offset:0xe00
	s_waitcnt lgkmcnt(6)
	v_mfma_f32_32x32x16_bf16 v[16:31], v[146:149], v[194:197], v[16:31]
	ds_read_b64_tr_b16 v[194:195], v161 offset:0x1600
	ds_read_b64_tr_b16 v[196:197], v161 offset:0x1e00
	s_waitcnt lgkmcnt(6)
	v_mfma_f32_32x32x16_bf16 v[16:31], v[150:153], v[198:201], v[16:31]
	ds_read_b64_tr_b16 v[198:199], v161 offset:0x2600
	ds_read_b64_tr_b16 v[200:201], v161 offset:0x2e00
	s_waitcnt lgkmcnt(6)
	v_mfma_f32_32x32x16_bf16 v[16:31], v[154:157], v[202:205], v[16:31]
	ds_read_b64_tr_b16 v[202:203], v161 offset:0x3600
	ds_read_b64_tr_b16 v[204:205], v161 offset:0x3e00
	s_waitcnt lgkmcnt(6)
	v_mfma_f32_32x32x16_bf16 v[0:15], v[142:145], v[190:193], v[0:15]
	v_max_f32_e32 v142, v81, v81
	v_max_f32_e32 v143, v80, v80
	v_max_f32_e32 v142, v143, v142
	v_max3_f32 v142, v142, v82, v83
	v_max3_f32 v142, v142, v84, v85
	v_max3_f32 v142, v142, v86, v87
	v_max3_f32 v142, v142, v88, v89
	v_max3_f32 v142, v142, v90, v91
	v_max3_f32 v142, v142, v92, v93
	s_waitcnt lgkmcnt(4)
	v_mfma_f32_32x32x16_bf16 v[0:15], v[146:149], v[194:197], v[0:15]
	v_max3_f32 v142, v142, v94, v95
	v_max3_f32 v142, v142, v64, v65
	v_max3_f32 v142, v142, v66, v67
	v_max3_f32 v142, v142, v68, v69
	v_max3_f32 v142, v142, v70, v71
	v_max3_f32 v142, v142, v72, v73
	v_max3_f32 v142, v142, v74, v75
	v_max3_f32 v142, v142, v76, v77
	s_waitcnt lgkmcnt(2)
	v_mfma_f32_32x32x16_bf16 v[0:15], v[150:153], v[198:201], v[0:15]
	v_max3_f32 v142, v142, v78, v79
	v_mov_b32_e32 v143, v142
	s_nop 1
	v_permlane32_swap_b32_e32 v142, v143
	v_max_f32_e32 v143, v143, v143
	v_max_f32_e32 v142, v142, v142
	v_max_f32_e32 v142, v142, v143
	v_sub_f32_e32 v143, v142, v160
	v_cmp_ge_f32_e32 vcc, s45, v143
	v_max_f32_e32 v143, v160, v160
	v_max_f32_e32 v142, v143, v142
	s_waitcnt lgkmcnt(0)
	v_mfma_f32_32x32x16_bf16 v[0:15], v[154:157], v[202:205], v[0:15]
	s_setprio 1
	v_sub_f32_e32 v143, v160, v142
	v_mul_f32_e32 v143, 0x3dd53b94, v143
	v_exp_f32_e32 v143, v143
	s_cmp_eq_u64 vcc, exec
	s_cselect_b64 s[38:39], -1, 0
	v_cndmask_b32_e64 v190, v143, 1.0, s[38:39]
	v_cmp_gt_f32_e32 vcc, 1.0, v190
	s_cbranch_vccz .LBB0_321
; #define SBAR() __builtin_amdgcn_sched_barrier(0)
; #define RESC(a) do { if (__any((a) < 1.f)) { if (hi == 0) al_l[r32] = (a); asm volatile("s_waitcnt lgkmcnt(0)" ::: "memory"); \
;     for (int d = 0; d < 4; ++d) for (int r = 0; r < 16; ++r) o[d][r] *= al_l[crow(r, hi)]; } } while (0)
; #define ISSUE_K(j, stg) do { const long _k0 = TROW(j); const char* _kt = (const char*)Kh + _k0 * (LDK * 2); _Pragma("unroll") for (int _i = 0; _i < 3; ++_i) \
;     __builtin_amdgcn_global_load_lds((const unsigned*)(_kt + okk[_i]), (LAS unsigned*)(ldsL + A2_K + (stg) * SHM_K + (wid * 3 + _i) * 1024), 16, 0, 0); } while (0)
; #define ISSUE_V(j, stg) do { const long _k0 = TROW(j); const char* _vt = (const char*)Vh + _k0 * (LDV * 2); _Pragma("unroll") for (int _i = 0; _i < 2; ++_i) \
;     __builtin_amdgcn_global_load_lds((const unsigned*)(_vt + ovv[_i]), (LAS unsigned*)(ldsL + (stg) * SHM_V + (wid * 2 + _i) * 1024), 16, 0, 0); } while (0)
; #define WAITV(n) asm volatile("s_waitcnt vmcnt(" #n ")" ::: "memory")
; #define ABAR() do { asm volatile("s_waitcnt lgkmcnt(0)" ::: "memory"); __builtin_amdgcn_s_barrier(); asm volatile("" ::: "memory"); } while (0)
; __device__ __forceinline__ void partialSM(f32x16& p0, f32x16& p1, float& m_reg, float& mn, float& alpha) {
;     ...
;   const float mnC = -mn * C;
; #pragma unroll
;   for (int r = 0; r < 16; ++r) p0[r] = fmaf(p0[r], C, mnC);
; #pragma unroll
;   for (int r = 0; r < 16; ++r) p1[r] = fmaf(p1[r], C, mnC);
; #pragma unroll
;   for (int r = 0; r < 16; ++r) p0[r] = __builtin_amdgcn_exp2f(p0[r]);
; __device__ __forceinline__ void attn_body2(const bf16_t* __restrict__ Qb, const bf16_t* __restrict__ Kh, const bf16_t* __restrict__ Vh, ...
;     ...
;   f32x16 pA0, pA1, pB0, pB1; float mnA, mnB, alA, alB; bf16x8 pa0, pa1, pa2, pa3;
;   ISSUE_K(0, 0);
;   WAITV(0); ABAR();
;   ISSUE_K(1, 1); ISSUE_V(0, 0);
;   qkt(pA0, pA1, K_lds, qr, qx, r32, hi, 0); partialSM(pA0, pA1, m_reg, mnA, alA);
;   WAITV(0); ABAR();
;   for (int j = 1; j + 1 < NT; j += 2) {
;     ISSUE_K(j + 1, 0); ISSUE_V(j, 1);
;     SBAR(); qkt(pB0, pB1, K_lds + SHM_K, qr, qx, r32, hi, 0);
;     finishSM(pA0, pA1, alA, l_reg, pa0, pa1, pa2, pa3); SBAR();
;     pv_d0(o, vb0, pa0, pa1, pa2, pa3); partialSM(pB0, pB1, m_reg, mnB, alB);
;     RESC(alB); WAITV(0); ABAR();
;     ISSUE_K(j + 2, 1); ISSUE_V(j + 1, 0);
;     SBAR(); qkt(pA0, pA1, K_lds, qr, qx, r32, hi, (j + 1 == ntr) ? 1 : 0);
	s_and_saveexec_b64 s[60:61], s[36:37]
	ds_write_b32 v129, v190 offset:128
	s_or_b64 exec, exec, s[60:61]
	s_waitcnt lgkmcnt(0)
	v_add_u32_e32 v143, s87, v128
	ds_read_b128 v[144:147], v143 offset:224
	ds_read_b128 v[148:151], v143 offset:192
	ds_read_b128 v[152:155], v143 offset:160
	ds_read_b128 v[192:195], v143 offset:128
	s_waitcnt lgkmcnt(0)
	v_pk_mul_f32 v[60:61], v[60:61], v[144:145]
	v_pk_mul_f32 v[56:57], v[56:57], v[148:149]
	v_pk_mul_f32 v[52:53], v[52:53], v[152:153]
	v_pk_mul_f32 v[62:63], v[62:63], v[146:147]
	v_pk_mul_f32 v[58:59], v[58:59], v[150:151]
	v_pk_mul_f32 v[54:55], v[54:55], v[154:155]
	v_pk_mul_f32 v[50:51], v[50:51], v[194:195]
	v_pk_mul_f32 v[48:49], v[48:49], v[192:193]
	v_pk_mul_f32 v[44:45], v[44:45], v[144:145]
	v_pk_mul_f32 v[40:41], v[40:41], v[148:149]
	v_pk_mul_f32 v[36:37], v[36:37], v[152:153]
	v_pk_mul_f32 v[46:47], v[46:47], v[146:147]
	v_pk_mul_f32 v[42:43], v[42:43], v[150:151]
	v_pk_mul_f32 v[38:39], v[38:39], v[154:155]
	v_pk_mul_f32 v[34:35], v[34:35], v[194:195]
	v_pk_mul_f32 v[32:33], v[32:33], v[192:193]
	v_pk_mul_f32 v[28:29], v[28:29], v[144:145]
	v_pk_mul_f32 v[24:25], v[24:25], v[148:149]
	v_pk_mul_f32 v[20:21], v[20:21], v[152:153]
	v_pk_mul_f32 v[30:31], v[30:31], v[146:147]
	v_pk_mul_f32 v[26:27], v[26:27], v[150:151]
	v_pk_mul_f32 v[22:23], v[22:23], v[154:155]
	v_pk_mul_f32 v[18:19], v[18:19], v[194:195]
	v_pk_mul_f32 v[16:17], v[16:17], v[192:193]
	v_pk_mul_f32 v[12:13], v[12:13], v[144:145]
	v_pk_mul_f32 v[8:9], v[8:9], v[148:149]
	v_pk_mul_f32 v[4:5], v[4:5], v[152:153]
	v_pk_mul_f32 v[14:15], v[14:15], v[146:147]
	v_pk_mul_f32 v[10:11], v[10:11], v[150:151]
	v_pk_mul_f32 v[6:7], v[6:7], v[154:155]
	v_pk_mul_f32 v[2:3], v[2:3], v[194:195]
	v_pk_mul_f32 v[0:1], v[0:1], v[192:193]
.LBB0_321:
	s_ashr_i32 s59, s58, 31
	s_add_i32 s63, s63, 2
	s_cmp_lt_u32 s63, s84
	v_cndmask_b32_e64 v160, v142, v160, s[38:39]
	s_cselect_b32 s38, 0, s84
	s_cselect_b32 s39, s2, s83
	s_lshl_b32 s38, s38, 6
	s_sub_i32 s38, s39, s38
	s_add_i32 s38, s52, s38
	s_add_i32 s38, s38, 64
	s_mul_hi_i32 s39, s38, 0xc00
	s_mulk_i32 s38, 0xc00
	s_add_u32 s38, s30, s38
	v_mul_f32_e32 v142, 0xbdd53b94, v160
	s_waitcnt vmcnt(0)
	s_addc_u32 s39, s31, s39
	v_fmamk_f32 v192, v64, 0x3dd53b94, v142
	v_fmamk_f32 v193, v65, 0x3dd53b94, v142
	s_waitcnt lgkmcnt(0)
	s_barrier
	v_lshl_add_u64 v[64:65], s[38:39], 0, v[132:133]
	s_mov_b32 m0, s94
	v_fmamk_f32 v80, v80, 0x3dd53b94, v142
	global_load_lds_dwordx4 v[64:65], off
	v_lshl_add_u64 v[64:65], s[38:39], 0, v[130:131]
	s_mov_b32 m0, s75
	v_fmamk_f32 v81, v81, 0x3dd53b94, v142
	global_load_lds_dwordx4 v[64:65], off
	v_lshl_add_u64 v[64:65], s[38:39], 0, v[136:137]
	s_mov_b32 m0, s76
	s_lshl_b64 s[38:39], s[58:59], 11
	global_load_lds_dwordx4 v[64:65], off
	v_lshl_add_u64 v[64:65], v[140:141], 0, s[38:39]
	s_mov_b32 m0, s3
	v_fmamk_f32 v82, v82, 0x3dd53b94, v142
	global_load_lds_dwordx4 v[64:65], off
	v_lshl_add_u64 v[64:65], v[64:65], 0, s[22:23]
	s_mov_b32 m0, s29
	v_fmamk_f32 v83, v83, 0x3dd53b94, v142
	global_load_lds_dwordx4 v[64:65], off
	v_fmamk_f32 v84, v84, 0x3dd53b94, v142
	v_fmamk_f32 v85, v85, 0x3dd53b94, v142
	v_fmamk_f32 v86, v86, 0x3dd53b94, v142
	v_fmamk_f32 v87, v87, 0x3dd53b94, v142
	v_fmamk_f32 v88, v88, 0x3dd53b94, v142
	v_fmamk_f32 v89, v89, 0x3dd53b94, v142
	v_fmamk_f32 v90, v90, 0x3dd53b94, v142
	v_fmamk_f32 v91, v91, 0x3dd53b94, v142
	v_fmamk_f32 v92, v92, 0x3dd53b94, v142
	v_fmamk_f32 v93, v93, 0x3dd53b94, v142
	v_fmamk_f32 v94, v94, 0x3dd53b94, v142
	v_fmamk_f32 v95, v95, 0x3dd53b94, v142
	v_fmamk_f32 v194, v66, 0x3dd53b94, v142
	v_fmamk_f32 v195, v67, 0x3dd53b94, v142
	v_fmamk_f32 v196, v68, 0x3dd53b94, v142
	v_fmamk_f32 v197, v69, 0x3dd53b94, v142
	v_fmamk_f32 v198, v70, 0x3dd53b94, v142
	v_fmamk_f32 v199, v71, 0x3dd53b94, v142
	v_fmamk_f32 v200, v72, 0x3dd53b94, v142
	v_fmamk_f32 v201, v73, 0x3dd53b94, v142
	v_fmamk_f32 v202, v74, 0x3dd53b94, v142
	v_fmamk_f32 v203, v75, 0x3dd53b94, v142
	v_fmamk_f32 v204, v76, 0x3dd53b94, v142
	v_fmamk_f32 v205, v77, 0x3dd53b94, v142
	v_fmamk_f32 v206, v78, 0x3dd53b94, v142
	v_fmamk_f32 v207, v79, 0x3dd53b94, v142
	v_exp_f32_e32 v151, v80
	v_exp_f32_e32 v152, v81
	v_exp_f32_e32 v153, v82
	v_exp_f32_e32 v154, v83
	v_exp_f32_e32 v155, v84
	v_exp_f32_e32 v156, v85
	v_exp_f32_e32 v157, v86
	v_exp_f32_e32 v191, v87
	v_exp_f32_e32 v143, v88
	v_exp_f32_e32 v144, v89
	v_exp_f32_e32 v145, v90
	v_exp_f32_e32 v146, v91
	v_exp_f32_e32 v147, v92
	v_exp_f32_e32 v148, v93
	v_exp_f32_e32 v149, v94
	v_exp_f32_e32 v150, v95
	s_setprio 0
	ds_read_b128 v[64:67], v174 offset:24576
	ds_read_b128 v[80:83], v174 offset:36864
	ds_read_b128 v[208:211], v166 offset:24576
	ds_read_b128 v[212:215], v166 offset:36864
	ds_read_b128 v[176:179], v162 offset:24576
	ds_read_b128 v[180:183], v162 offset:36864
	s_cmp_eq_u32 s12, s84
	s_cselect_b64 vcc, -1, 0
	s_waitcnt lgkmcnt(4)
	v_mfma_f32_32x32x16_bf16 v[64:79], v[64:67], v[96:99], 0
	v_mfma_f32_32x32x16_bf16 v[80:95], v[80:83], v[96:99], 0
	s_waitcnt lgkmcnt(2)
	v_mfma_f32_32x32x16_bf16 v[64:79], v[208:211], v[100:103], v[64:79]
	v_mfma_f32_32x32x16_bf16 v[80:95], v[212:215], v[100:103], v[80:95]
	ds_read_b128 v[208:211], v163 offset:24576
	ds_read_b128 v[212:215], v163 offset:36864
	s_waitcnt lgkmcnt(2)
	v_mfma_f32_32x32x16_bf16 v[64:79], v[176:179], v[104:107], v[64:79]
	v_mfma_f32_32x32x16_bf16 v[80:95], v[180:183], v[104:107], v[80:95]
	ds_read_b128 v[176:179], v164 offset:24576
	ds_read_b128 v[180:183], v164 offset:36864
	s_waitcnt lgkmcnt(2)
	v_mfma_f32_32x32x16_bf16 v[64:79], v[208:211], v[108:111], v[64:79]
	v_mfma_f32_32x32x16_bf16 v[80:95], v[212:215], v[108:111], v[80:95]
	ds_read_b128 v[208:211], v165 offset:24576
	ds_read_b128 v[212:215], v165 offset:36864
	s_waitcnt lgkmcnt(2)
; __device__ __forceinline__ void finishSM(f32x16& p0, f32x16& p1, float alpha, float& l_reg, bf16x8& pa0, bf16x8& pa1, bf16x8& pa2, bf16x8& pa3) {
; #pragma unroll
;   for (int r = 0; r < 16; ++r) p1[r] = __builtin_amdgcn_exp2f(p1[r]);
;   float ps = 0;
; #pragma unroll
;   for (int r = 0; r < 16; ++r) ps += p0[r];
; #pragma unroll
;   for (int r = 0; r < 16; ++r) ps += p1[r];
;   { auto rr = __builtin_amdgcn_permlane32_swap(__float_as_uint(ps), __float_as_uint(ps), false, false);
;     ps = __uint_as_float(rr[0]) + __uint_as_float(rr[1]); }
;   l_reg = l_reg * alpha + ps;
;     ...
;   PK4(p0, 0, pa0); PK4(p0, 8, pa1); PK4(p1, 0, pa2); PK4(p1, 8, pa3);
;     ...
; }
; __device__ __forceinline__ void qkt(f32x16& p0, f32x16& p1, const char* Ks, const bf16x8* qr, const char* qx, int r32, int hi, int mode) {
;   p0 = f32x16{}; p1 = f32x16{};
; #pragma unroll
;   for (int d0 = 0; d0 < 12; ++d0) { const int cb = (d0 * 16 + hi * 8) * 2;
;     bf16x8 b0 = *reinterpret_cast<const bf16x8*>(Ks + KSWZ(r32, cb));
;     bf16x8 b1 = *reinterpret_cast<const bf16x8*>(Ks + KSWZ(32 + r32, cb));
;     const bf16x8 qf = d0 < 8 ? qr[d0 < 8 ? d0 : 0] : *reinterpret_cast<const bf16x8*>(qx + (d0 - 8) * 1024);
;     p0 = __builtin_amdgcn_mfma_f32_32x32x16_bf16(b0, qf, p0, 0, 0, 0);
;     p1 = __builtin_amdgcn_mfma_f32_32x32x16_bf16(b1, qf, p1, 0, 0, 0); }
;   if (mode != 0) {
;     constexpr float NEG = -1e30f;
; #pragma unroll
;     for (int r = 0; r < 16; ++r) p1[r] = NEG;
; #pragma unroll
;     for (int r = 8; r < 16; ++r) p0[r] = NEG;
;     if (mode == 2) {
; #pragma unroll
;       for (int r = 0; r < 8; ++r) p0[r] = NEG; }
;   }
	v_mfma_f32_32x32x16_bf16 v[64:79], v[176:179], v[112:115], v[64:79]
	v_mfma_f32_32x32x16_bf16 v[80:95], v[180:183], v[112:115], v[80:95]
	ds_read_b128 v[176:179], v167 offset:24576
	ds_read_b128 v[180:183], v167 offset:36864
	s_waitcnt lgkmcnt(2)
	v_mfma_f32_32x32x16_bf16 v[64:79], v[208:211], v[116:119], v[64:79]
	v_mfma_f32_32x32x16_bf16 v[80:95], v[212:215], v[116:119], v[80:95]
	ds_read_b128 v[208:211], v168 offset:24576
	ds_read_b128 v[212:215], v168 offset:36864
	s_waitcnt lgkmcnt(2)
	v_mfma_f32_32x32x16_bf16 v[64:79], v[176:179], v[120:123], v[64:79]
	v_mfma_f32_32x32x16_bf16 v[80:95], v[180:183], v[120:123], v[80:95]
	ds_read_b128 v[176:179], v169 offset:24576
	ds_read_b128 v[180:183], v169 offset:36864
	ds_read_b128 v[184:187], v173
	s_waitcnt lgkmcnt(3)
	v_mfma_f32_32x32x16_bf16 v[64:79], v[208:211], v[124:127], v[64:79]
	v_mfma_f32_32x32x16_bf16 v[80:95], v[212:215], v[124:127], v[80:95]
	ds_read_b128 v[208:211], v170 offset:24576
	ds_read_b128 v[212:215], v170 offset:36864
	ds_read_b128 v[216:219], v173 offset:1024
	s_waitcnt lgkmcnt(3)
	v_mfma_f32_32x32x16_bf16 v[64:79], v[176:179], v[184:187], v[64:79]
	v_mfma_f32_32x32x16_bf16 v[80:95], v[180:183], v[184:187], v[80:95]
	ds_read_b128 v[176:179], v171 offset:24576
	ds_read_b128 v[180:183], v171 offset:36864
	ds_read_b128 v[184:187], v173 offset:2048
	s_waitcnt lgkmcnt(3)
	v_mfma_f32_32x32x16_bf16 v[64:79], v[208:211], v[216:219], v[64:79]
	v_mfma_f32_32x32x16_bf16 v[80:95], v[212:215], v[216:219], v[80:95]
	ds_read_b128 v[208:211], v172 offset:24576
	ds_read_b128 v[212:215], v172 offset:36864
	ds_read_b128 v[216:219], v173 offset:3072
	s_waitcnt lgkmcnt(3)
	v_mfma_f32_32x32x16_bf16 v[64:79], v[176:179], v[184:187], v[64:79]
	v_mfma_f32_32x32x16_bf16 v[80:95], v[180:183], v[184:187], v[80:95]
	s_waitcnt lgkmcnt(0)
	v_mfma_f32_32x32x16_bf16 v[64:79], v[208:211], v[216:219], v[64:79]
	v_mfma_f32_32x32x16_bf16 v[80:95], v[212:215], v[216:219], v[80:95]
	s_setprio 1
	s_nop 10
	v_cndmask_b32_e32 v208, v79, v229, vcc
	v_cndmask_b32_e32 v209, v78, v229, vcc
	v_cndmask_b32_e32 v210, v77, v229, vcc
	v_cndmask_b32_e32 v211, v76, v229, vcc
	v_cndmask_b32_e32 v212, v75, v229, vcc
	v_cndmask_b32_e32 v213, v74, v229, vcc
	v_cndmask_b32_e32 v214, v73, v229, vcc
	v_cndmask_b32_e32 v79, v89, v229, vcc
	v_add_f32_e32 v89, 0, v151
	v_add_f32_e32 v89, v152, v89
	v_add_f32_e32 v89, v153, v89
	v_add_f32_e32 v89, v154, v89
	v_add_f32_e32 v89, v155, v89
	v_add_f32_e32 v89, v156, v89
	v_add_f32_e32 v89, v157, v89
	v_add_f32_e32 v89, v191, v89
	v_add_f32_e32 v89, v143, v89
	v_add_f32_e32 v89, v144, v89
	v_add_f32_e32 v89, v145, v89
	v_add_f32_e32 v89, v146, v89
	v_cndmask_b32_e32 v78, v88, v229, vcc
	v_exp_f32_e32 v88, v192
	v_add_f32_e32 v89, v147, v89
	v_cndmask_b32_e32 v77, v91, v229, vcc
	v_exp_f32_e32 v91, v193
	v_add_f32_e32 v89, v148, v89
	v_exp_f32_e32 v192, v194
	v_add_f32_e32 v89, v149, v89
	v_exp_f32_e32 v193, v195
	v_add_f32_e32 v89, v150, v89
	v_exp_f32_e32 v194, v196
	v_add_f32_e32 v89, v88, v89
	v_exp_f32_e32 v195, v197
	v_add_f32_e32 v89, v91, v89
	v_exp_f32_e32 v196, v198
	v_add_f32_e32 v89, v192, v89
	v_exp_f32_e32 v197, v199
	v_add_f32_e32 v89, v193, v89
	v_exp_f32_e32 v198, v200
	v_add_f32_e32 v89, v194, v89
	v_exp_f32_e32 v199, v201
	v_add_f32_e32 v89, v195, v89
	v_exp_f32_e32 v200, v202
	v_add_f32_e32 v89, v196, v89
	v_exp_f32_e32 v201, v203
	v_add_f32_e32 v89, v197, v89
	v_exp_f32_e32 v202, v204
	v_add_f32_e32 v89, v198, v89
	v_exp_f32_e32 v203, v205
	v_add_f32_e32 v89, v199, v89
	v_exp_f32_e32 v204, v206
	v_add_f32_e32 v89, v200, v89
	v_exp_f32_e32 v205, v207
	v_add_f32_e32 v89, v201, v89
	v_add_f32_e32 v89, v202, v89
	v_add_f32_e32 v89, v203, v89
	v_add_f32_e32 v89, v204, v89
	v_add_f32_e32 v89, v205, v89
	v_cndmask_b32_e32 v76, v90, v229, vcc
	v_mov_b32_e32 v90, v89
	v_cndmask_b32_e32 v215, v72, v229, vcc
	v_cndmask_b32_e32 v73, v95, v229, vcc
	v_cndmask_b32_e32 v72, v94, v229, vcc
	v_cndmask_b32_e32 v75, v93, v229, vcc
	v_cndmask_b32_e32 v74, v92, v229, vcc
	v_cndmask_b32_e32 v87, v87, v229, vcc
	v_cndmask_b32_e32 v86, v86, v229, vcc
	v_cndmask_b32_e32 v85, v85, v229, vcc
	v_cndmask_b32_e32 v84, v84, v229, vcc
	v_cndmask_b32_e32 v83, v83, v229, vcc
	v_cndmask_b32_e32 v82, v82, v229, vcc
	v_cndmask_b32_e32 v81, v81, v229, vcc
	v_cndmask_b32_e32 v80, v80, v229, vcc
	v_permlane32_swap_b32_e32 v89, v90
	v_cvt_pk_bf16_f32 v92, v151, v152
	v_cvt_pk_bf16_f32 v93, v153, v154
	v_cvt_pk_bf16_f32 v94, v155, v156
	v_cvt_pk_bf16_f32 v95, v157, v191
	v_cvt_pk_bf16_f32 v144, v143, v144
	v_cvt_pk_bf16_f32 v145, v145, v146
	v_cvt_pk_bf16_f32 v146, v147, v148
	v_cvt_pk_bf16_f32 v147, v149, v150
	v_cvt_pk_bf16_f32 v148, v88, v91
	v_cvt_pk_bf16_f32 v149, v192, v193
	v_cvt_pk_bf16_f32 v150, v194, v195
	v_cvt_pk_bf16_f32 v151, v196, v197
	v_cvt_pk_bf16_f32 v152, v198, v199
	v_cvt_pk_bf16_f32 v153, v200, v201
	v_cvt_pk_bf16_f32 v154, v202, v203
	v_cvt_pk_bf16_f32 v155, v204, v205
	v_permlane32_swap_b32_e32 v92, v94
	v_permlane32_swap_b32_e32 v93, v95
	v_permlane32_swap_b32_e32 v144, v146
	v_permlane32_swap_b32_e32 v145, v147
	v_permlane32_swap_b32_e32 v148, v150
	v_permlane32_swap_b32_e32 v149, v151
	v_permlane32_swap_b32_e32 v152, v154
	v_permlane32_swap_b32_e32 v153, v155
	s_setprio 0
	ds_read_b64_tr_b16 v[192:193], v159 offset:0
	ds_read_b64_tr_b16 v[194:195], v159 offset:0x800
	ds_read_b64_tr_b16 v[196:197], v159 offset:0x1000
	ds_read_b64_tr_b16 v[198:199], v159 offset:0x1800
	ds_read_b64_tr_b16 v[200:201], v159 offset:0x2000
	ds_read_b64_tr_b16 v[202:203], v159 offset:0x2800
	ds_read_b64_tr_b16 v[204:205], v159 offset:0x3000
	ds_read_b64_tr_b16 v[206:207], v159 offset:0x3800
	s_waitcnt lgkmcnt(6)
; #define SBAR() __builtin_amdgcn_sched_barrier(0)
; __device__ __forceinline__ void partialSM(f32x16& p0, f32x16& p1, float& m_reg, float& mn, float& alpha) {
;   constexpr float C = ATT_SCALE * 1.4426950408889634f;
;   float pmax = p0[0];
; #pragma unroll
;   for (int r = 1; r < 16; ++r) pmax = fmaxf(pmax, p0[r]);
; #pragma unroll
;   for (int r = 0; r < 16; ++r) pmax = fmaxf(pmax, p1[r]);
;   { auto rr = __builtin_amdgcn_permlane32_swap(__float_as_uint(pmax), __float_as_uint(pmax), false, false);
;     pmax = fmaxf(__uint_as_float(rr[0]), __uint_as_float(rr[1])); }
;   if (__builtin_expect(__all(pmax - m_reg <= ATT_THR / ATT_SCALE), 1)) { mn = m_reg; alpha = 1.f; }
;   else { mn = fmaxf(m_reg, pmax); alpha = __builtin_amdgcn_exp2f((m_reg - mn) * C); m_reg = mn; }
; template <int D0> __device__ __forceinline__ void pv_one(f32x16& od, int vb, bf16x8 pa0, bf16x8 pa1, bf16x8 pa2, bf16x8 pa3) {
;   const s16x4 l0 = tr_read<v_rd_off(D0, 0, 0)>(vb), h0 = tr_read<v_rd_off(D0, 0, 1)>(vb), l1 = tr_read<v_rd_off(D0, 1, 0)>(vb), h1 = tr_read<v_rd_off(D0, 1, 1)>(vb);
;   const s16x4 l2 = tr_read<v_rd_off(D0, 2, 0)>(vb), h2 = tr_read<v_rd_off(D0, 2, 1)>(vb), l3 = tr_read<v_rd_off(D0, 3, 0)>(vb), h3 = tr_read<v_rd_off(D0, 3, 1)>(vb);
;   asm volatile("s_waitcnt lgkmcnt(0)" ::: "memory"); SBAR();
;     ...
;   od = __builtin_amdgcn_mfma_f32_32x32x16_bf16(pa0, PK(l0, h0), od, 0, 0, 0);
;   od = __builtin_amdgcn_mfma_f32_32x32x16_bf16(pa1, PK(l1, h1), od, 0, 0, 0);
;   od = __builtin_amdgcn_mfma_f32_32x32x16_bf16(pa2, PK(l2, h2), od, 0, 0, 0);
;   od = __builtin_amdgcn_mfma_f32_32x32x16_bf16(pa3, PK(l3, h3), od, 0, 0, 0);
;     ...
; }
; __device__ __forceinline__ void pv_d0(f32x16* o, int vb, bf16x8 pa0, bf16x8 pa1, bf16x8 pa2, bf16x8 pa3) {
;   pv_one<0>(o[0], vb, pa0, pa1, pa2, pa3); pv_one<1>(o[1], vb, pa0, pa1, pa2, pa3); pv_one<2>(o[2], vb, pa0, pa1, pa2, pa3); pv_one<3>(o[3], vb, pa0, pa1, pa2, pa3);
	s_nop 0
	v_mfma_f32_32x32x16_bf16 v[48:63], v[92:95], v[192:195], v[48:63]
	ds_read_b64_tr_b16 v[192:193], v159 offset:0x200
	ds_read_b64_tr_b16 v[194:195], v159 offset:0xa00
	s_waitcnt lgkmcnt(6)
	v_mfma_f32_32x32x16_bf16 v[48:63], v[144:147], v[196:199], v[48:63]
	ds_read_b64_tr_b16 v[196:197], v159 offset:0x1200
	ds_read_b64_tr_b16 v[198:199], v159 offset:0x1a00
	s_waitcnt lgkmcnt(6)
	v_mfma_f32_32x32x16_bf16 v[48:63], v[148:151], v[200:203], v[48:63]
	ds_read_b64_tr_b16 v[200:201], v159 offset:0x2200
	ds_read_b64_tr_b16 v[202:203], v159 offset:0x2a00
	s_waitcnt lgkmcnt(6)
	v_mfma_f32_32x32x16_bf16 v[48:63], v[152:155], v[204:207], v[48:63]
	ds_read_b64_tr_b16 v[204:205], v159 offset:0x3200
	ds_read_b64_tr_b16 v[206:207], v159 offset:0x3a00
	s_waitcnt lgkmcnt(6)
	v_mfma_f32_32x32x16_bf16 v[32:47], v[92:95], v[192:195], v[32:47]
	ds_read_b64_tr_b16 v[192:193], v159 offset:0x400
	ds_read_b64_tr_b16 v[194:195], v159 offset:0xc00
	s_waitcnt lgkmcnt(6)
	v_mfma_f32_32x32x16_bf16 v[32:47], v[144:147], v[196:199], v[32:47]
	ds_read_b64_tr_b16 v[196:197], v159 offset:0x1400
	ds_read_b64_tr_b16 v[198:199], v159 offset:0x1c00
	s_waitcnt lgkmcnt(6)
	v_mfma_f32_32x32x16_bf16 v[32:47], v[148:151], v[200:203], v[32:47]
	ds_read_b64_tr_b16 v[200:201], v159 offset:0x2400
	ds_read_b64_tr_b16 v[202:203], v159 offset:0x2c00
	s_waitcnt lgkmcnt(6)
	v_mfma_f32_32x32x16_bf16 v[32:47], v[152:155], v[204:207], v[32:47]
	ds_read_b64_tr_b16 v[204:205], v159 offset:0x3400
	ds_read_b64_tr_b16 v[206:207], v159 offset:0x3c00
	s_waitcnt lgkmcnt(6)
	v_mfma_f32_32x32x16_bf16 v[16:31], v[92:95], v[192:195], v[16:31]
	ds_read_b64_tr_b16 v[192:193], v159 offset:0x600
	ds_read_b64_tr_b16 v[194:195], v159 offset:0xe00
	s_waitcnt lgkmcnt(6)
	v_mfma_f32_32x32x16_bf16 v[16:31], v[144:147], v[196:199], v[16:31]
	ds_read_b64_tr_b16 v[196:197], v159 offset:0x1600
	ds_read_b64_tr_b16 v[198:199], v159 offset:0x1e00
	s_waitcnt lgkmcnt(6)
	v_mfma_f32_32x32x16_bf16 v[16:31], v[148:151], v[200:203], v[16:31]
	ds_read_b64_tr_b16 v[200:201], v159 offset:0x2600
	ds_read_b64_tr_b16 v[202:203], v159 offset:0x2e00
	s_waitcnt lgkmcnt(6)
	v_mfma_f32_32x32x16_bf16 v[16:31], v[152:155], v[204:207], v[16:31]
	ds_read_b64_tr_b16 v[204:205], v159 offset:0x3600
	ds_read_b64_tr_b16 v[206:207], v159 offset:0x3e00
	s_waitcnt lgkmcnt(6)
	v_mfma_f32_32x32x16_bf16 v[0:15], v[92:95], v[192:195], v[0:15]
	v_max_f32_e32 v88, v65, v65
	v_max_f32_e32 v91, v64, v64
	v_max_f32_e32 v88, v91, v88
	v_max3_f32 v88, v88, v66, v67
	v_max3_f32 v88, v88, v68, v69
	v_max3_f32 v88, v88, v70, v71
	v_max3_f32 v88, v88, v215, v214
	s_waitcnt lgkmcnt(4)
	v_mfma_f32_32x32x16_bf16 v[0:15], v[144:147], v[196:199], v[0:15]
	v_max3_f32 v88, v88, v213, v212
	v_max3_f32 v88, v88, v211, v210
	v_max3_f32 v88, v88, v209, v208
	v_max3_f32 v88, v88, v80, v81
	v_max3_f32 v88, v88, v82, v83
	v_max3_f32 v88, v88, v84, v85
	v_max3_f32 v88, v88, v86, v87
	s_waitcnt lgkmcnt(2)
	v_mfma_f32_32x32x16_bf16 v[0:15], v[148:151], v[200:203], v[0:15]
	v_max3_f32 v88, v88, v78, v79
	v_max3_f32 v88, v88, v76, v77
	v_max3_f32 v88, v88, v74, v75
	v_max3_f32 v88, v88, v72, v73
	v_mov_b32_e32 v91, v88
	s_nop 1
	v_permlane32_swap_b32_e32 v88, v91
	s_waitcnt lgkmcnt(0)
	v_mfma_f32_32x32x16_bf16 v[0:15], v[152:155], v[204:207], v[0:15]
	s_setprio 1
	v_max_f32_e32 v91, v91, v91
	v_max_f32_e32 v88, v88, v88
	v_max_f32_e32 v91, v88, v91
	v_sub_f32_e32 v88, v91, v160
	v_cmp_ge_f32_e32 vcc, s45, v88
	v_mov_b32_e32 v88, 1.0
	s_cmp_eq_u64 vcc, exec
	s_cbranch_scc0 .LBB0_328
	v_cmp_gt_f32_e32 vcc, 1.0, v88
	s_cbranch_vccz .LBB0_326

; #define SBAR() __builtin_amdgcn_sched_barrier(0)
; __device__ __forceinline__ void finishSM(f32x16& p0, f32x16& p1, float alpha, float& l_reg, bf16x8& pa0, bf16x8& pa1, bf16x8& pa2, bf16x8& pa3) {
; #pragma unroll
;   for (int r = 0; r < 16; ++r) p1[r] = __builtin_amdgcn_exp2f(p1[r]);
;   float ps = 0;
; #pragma unroll
;   for (int r = 0; r < 16; ++r) ps += p0[r];
; #pragma unroll
;   for (int r = 0; r < 16; ++r) ps += p1[r];
;   { auto rr = __builtin_amdgcn_permlane32_swap(__float_as_uint(ps), __float_as_uint(ps), false, false);
;     ps = __uint_as_float(rr[0]) + __uint_as_float(rr[1]); }
;   l_reg = l_reg * alpha + ps;
;     ...
;   PK4(p0, 0, pa0); PK4(p0, 8, pa1); PK4(p1, 0, pa2); PK4(p1, 8, pa3);
;     ...
; }
; template <int D0> __device__ __forceinline__ void pv_one(f32x16& od, int vb, bf16x8 pa0, bf16x8 pa1, bf16x8 pa2, bf16x8 pa3) {
;   const s16x4 l0 = tr_read<v_rd_off(D0, 0, 0)>(vb), h0 = tr_read<v_rd_off(D0, 0, 1)>(vb), l1 = tr_read<v_rd_off(D0, 1, 0)>(vb), h1 = tr_read<v_rd_off(D0, 1, 1)>(vb);
;   const s16x4 l2 = tr_read<v_rd_off(D0, 2, 0)>(vb), h2 = tr_read<v_rd_off(D0, 2, 1)>(vb), l3 = tr_read<v_rd_off(D0, 3, 0)>(vb), h3 = tr_read<v_rd_off(D0, 3, 1)>(vb);
;   asm volatile("s_waitcnt lgkmcnt(0)" ::: "memory"); SBAR();
;     ...
;   od = __builtin_amdgcn_mfma_f32_32x32x16_bf16(pa0, PK(l0, h0), od, 0, 0, 0);
;   od = __builtin_amdgcn_mfma_f32_32x32x16_bf16(pa1, PK(l1, h1), od, 0, 0, 0);
;   od = __builtin_amdgcn_mfma_f32_32x32x16_bf16(pa2, PK(l2, h2), od, 0, 0, 0);
;   od = __builtin_amdgcn_mfma_f32_32x32x16_bf16(pa3, PK(l3, h3), od, 0, 0, 0);
;     ...
; }
; __device__ __forceinline__ void pv_d0(f32x16* o, int vb, bf16x8 pa0, bf16x8 pa1, bf16x8 pa2, bf16x8 pa3) {
;   pv_one<0>(o[0], vb, pa0, pa1, pa2, pa3); pv_one<1>(o[1], vb, pa0, pa1, pa2, pa3); pv_one<2>(o[2], vb, pa0, pa1, pa2, pa3); pv_one<3>(o[3], vb, pa0, pa1, pa2, pa3);
.LattB_317:
	s_cmp_lt_u32 s12, s84
	s_cselect_b32 s38, 0, s84
	s_cselect_b32 s39, s2, s83
	s_lshl_b32 s38, s38, 6
	s_sub_i32 s38, s39, s38
	s_add_i32 s58, s52, s38
	s_mul_i32 s38, s58, 0xc00
	s_mul_hi_i32 s39, s58, 0xc00
	s_add_u32 s38, s30, s38
	s_addc_u32 s39, s31, s39
	s_mov_b32 m0, s95
	v_lshl_add_u64 v[64:65], s[38:39], 0, v[132:133]
	s_add_i32 s63, s12, -1
	global_load_lds_dwordx4 v[64:65], off
	v_lshl_add_u64 v[64:65], s[38:39], 0, v[130:131]
	s_mov_b32 m0, s96
	s_cmp_lt_u32 s63, s84
	global_load_lds_dwordx4 v[64:65], off
	v_lshl_add_u64 v[64:65], s[38:39], 0, v[136:137]
	s_cselect_b32 s38, 0, s84
	s_cselect_b32 s39, s2, s83
	s_lshl_b32 s38, s38, 6
	s_sub_i32 s38, s39, s38
	s_add_i32 s38, s52, s38
	s_sub_i32 s38, s38, 64
	s_ashr_i32 s39, s38, 31
	s_mov_b32 m0, s97
	s_lshl_b64 s[38:39], s[38:39], 11
	s_add_i32 s62, s3, 0x4000
	global_load_lds_dwordx4 v[64:65], off
	v_lshl_add_u64 v[64:65], v[140:141], 0, s[38:39]
	s_mov_b32 m0, s62
	s_add_i32 s56, s3, 0x4400
	global_load_lds_dwordx4 v[64:65], off
	v_lshl_add_u64 v[64:65], v[64:65], 0, s[22:23]
	s_mov_b32 m0, s56
	s_nop 0
	global_load_lds_dwordx4 v[64:65], off
	v_exp_f32_e32 v156, v156
	v_exp_f32_e32 v157, v157
	v_exp_f32_e32 v154, v154
	v_exp_f32_e32 v155, v155
	v_exp_f32_e32 v152, v152
	v_exp_f32_e32 v153, v153
	v_exp_f32_e32 v190, v150
	v_exp_f32_e32 v207, v151
	v_cvt_pk_bf16_f32 v150, v156, v157
	v_cvt_pk_bf16_f32 v151, v154, v155
	v_exp_f32_e32 v214, v142
	v_add_f32_e32 v142, 0, v199
	v_add_f32_e32 v142, v200, v142
	v_add_f32_e32 v142, v201, v142
	v_add_f32_e32 v142, v203, v142
	v_add_f32_e32 v142, v204, v142
	v_add_f32_e32 v142, v206, v142
	v_add_f32_e32 v142, v202, v142
	v_add_f32_e32 v142, v205, v142
	v_add_f32_e32 v142, v191, v142
	v_add_f32_e32 v142, v193, v142
	v_add_f32_e32 v142, v194, v142
	v_add_f32_e32 v142, v197, v142
	v_add_f32_e32 v142, v192, v142
	v_add_f32_e32 v142, v195, v142
	v_add_f32_e32 v142, v196, v142
	v_add_f32_e32 v142, v198, v142
	v_add_f32_e32 v142, v156, v142
	v_add_f32_e32 v142, v157, v142
	v_add_f32_e32 v142, v154, v142
	v_add_f32_e32 v142, v155, v142
	v_exp_f32_e32 v208, v148
	v_add_f32_e32 v142, v152, v142
	v_exp_f32_e32 v209, v149
	v_add_f32_e32 v142, v153, v142
	v_exp_f32_e32 v210, v146
	v_add_f32_e32 v142, v190, v142
	v_exp_f32_e32 v211, v147
	v_add_f32_e32 v142, v207, v142
	v_exp_f32_e32 v212, v144
	v_add_f32_e32 v142, v208, v142
	v_exp_f32_e32 v213, v145
	v_add_f32_e32 v142, v209, v142
	v_add_f32_e32 v142, v210, v142
	v_exp_f32_e32 v215, v143
	v_add_f32_e32 v142, v211, v142
	v_add_f32_e32 v142, v212, v142
	v_add_f32_e32 v142, v213, v142
	v_add_f32_e32 v142, v214, v142
	v_add_f32_e32 v188, v215, v142
	v_mov_b32_e32 v189, v188
	v_cvt_pk_bf16_f32 v142, v199, v200
	v_cvt_pk_bf16_f32 v144, v204, v206
	v_permlane32_swap_b32_e32 v188, v189
	v_cvt_pk_bf16_f32 v143, v201, v203
	v_cvt_pk_bf16_f32 v145, v202, v205
	v_permlane32_swap_b32_e32 v142, v144
	v_cvt_pk_bf16_f32 v146, v191, v193
	v_cvt_pk_bf16_f32 v147, v194, v197
	v_cvt_pk_bf16_f32 v148, v192, v195
	v_cvt_pk_bf16_f32 v149, v196, v198
	v_cvt_pk_bf16_f32 v152, v152, v153
	v_cvt_pk_bf16_f32 v153, v190, v207
	v_cvt_pk_bf16_f32 v154, v208, v209
	v_cvt_pk_bf16_f32 v155, v210, v211
	v_cvt_pk_bf16_f32 v156, v212, v213
	v_cvt_pk_bf16_f32 v157, v214, v215
	v_permlane32_swap_b32_e32 v143, v145
	v_permlane32_swap_b32_e32 v146, v148
	v_permlane32_swap_b32_e32 v147, v149
	v_permlane32_swap_b32_e32 v150, v152
	v_permlane32_swap_b32_e32 v151, v153
	v_permlane32_swap_b32_e32 v154, v156
	v_permlane32_swap_b32_e32 v155, v157
	s_setprio 0
	ds_read_b64_tr_b16 v[190:191], v161 offset:0
	ds_read_b64_tr_b16 v[192:193], v161 offset:0x800
	ds_read_b64_tr_b16 v[194:195], v161 offset:0x1000
	ds_read_b64_tr_b16 v[196:197], v161 offset:0x1800
	ds_read_b64_tr_b16 v[198:199], v161 offset:0x2000
	ds_read_b64_tr_b16 v[200:201], v161 offset:0x2800
	ds_read_b64_tr_b16 v[202:203], v161 offset:0x3000
	ds_read_b64_tr_b16 v[204:205], v161 offset:0x3800
	s_waitcnt lgkmcnt(6)
	s_nop 0
	v_mfma_f32_32x32x16_bf16 v[48:63], v[142:145], v[190:193], v[48:63]
	ds_read_b64_tr_b16 v[190:191], v161 offset:0x200
	ds_read_b64_tr_b16 v[192:193], v161 offset:0xa00
	s_waitcnt lgkmcnt(6)
	v_mfma_f32_32x32x16_bf16 v[48:63], v[146:149], v[194:197], v[48:63]
	ds_read_b64_tr_b16 v[194:195], v161 offset:0x1200
	ds_read_b64_tr_b16 v[196:197], v161 offset:0x1a00
	s_waitcnt lgkmcnt(6)
	v_mfma_f32_32x32x16_bf16 v[48:63], v[150:153], v[198:201], v[48:63]
	ds_read_b64_tr_b16 v[198:199], v161 offset:0x2200
	ds_read_b64_tr_b16 v[200:201], v161 offset:0x2a00
	s_waitcnt lgkmcnt(6)
	v_mfma_f32_32x32x16_bf16 v[48:63], v[154:157], v[202:205], v[48:63]
	ds_read_b64_tr_b16 v[202:203], v161 offset:0x3200
	ds_read_b64_tr_b16 v[204:205], v161 offset:0x3a00
	s_waitcnt lgkmcnt(6)
	v_mfma_f32_32x32x16_bf16 v[32:47], v[142:145], v[190:193], v[32:47]
	ds_read_b64_tr_b16 v[190:191], v161 offset:0x400
	ds_read_b64_tr_b16 v[192:193], v161 offset:0xc00
	s_waitcnt lgkmcnt(6)
	v_mfma_f32_32x32x16_bf16 v[32:47], v[146:149], v[194:197], v[32:47]
	ds_read_b64_tr_b16 v[194:195], v161 offset:0x1400
	ds_read_b64_tr_b16 v[196:197], v161 offset:0x1c00
	s_waitcnt lgkmcnt(6)
	v_mfma_f32_32x32x16_bf16 v[32:47], v[150:153], v[198:201], v[32:47]
	ds_read_b64_tr_b16 v[198:199], v161 offset:0x2400
	ds_read_b64_tr_b16 v[200:201], v161 offset:0x2c00
	s_waitcnt lgkmcnt(6)
	v_mfma_f32_32x32x16_bf16 v[32:47], v[154:157], v[202:205], v[32:47]
	ds_read_b64_tr_b16 v[202:203], v161 offset:0x3400
	ds_read_b64_tr_b16 v[204:205], v161 offset:0x3c00
	s_waitcnt lgkmcnt(6)
	v_mfma_f32_32x32x16_bf16 v[16:31], v[142:145], v[190:193], v[16:31]
	ds_read_b64_tr_b16 v[190:191], v161 offset:0x600
	ds_read_b64_tr_b16 v[192:193], v161 offset:0xe00
	s_waitcnt lgkmcnt(6)
; __device__ __forceinline__ void partialSM(f32x16& p0, f32x16& p1, float& m_reg, float& mn, float& alpha) {
;   constexpr float C = ATT_SCALE * 1.4426950408889634f;
;   float pmax = p0[0];
; #pragma unroll
;   for (int r = 1; r < 16; ++r) pmax = fmaxf(pmax, p0[r]);
; #pragma unroll
;   for (int r = 0; r < 16; ++r) pmax = fmaxf(pmax, p1[r]);
;   { auto rr = __builtin_amdgcn_permlane32_swap(__float_as_uint(pmax), __float_as_uint(pmax), false, false);
;     pmax = fmaxf(__uint_as_float(rr[0]), __uint_as_float(rr[1])); }
;   if (__builtin_expect(__all(pmax - m_reg <= ATT_THR / ATT_SCALE), 1)) { mn = m_reg; alpha = 1.f; }
;   else { mn = fmaxf(m_reg, pmax); alpha = __builtin_amdgcn_exp2f((m_reg - mn) * C); m_reg = mn; }
; __device__ __forceinline__ void qkt(f32x16& p0, f32x16& p1, const char* Ks, const bf16x8* qr, const char* qx, int r32, int hi, int mode) {
;   p0 = f32x16{}; p1 = f32x16{};
; #pragma unroll
;   for (int d0 = 0; d0 < 12; ++d0) { const int cb = (d0 * 16 + hi * 8) * 2;
;     bf16x8 b0 = *reinterpret_cast<const bf16x8*>(Ks + KSWZ(r32, cb));
;     bf16x8 b1 = *reinterpret_cast<const bf16x8*>(Ks + KSWZ(32 + r32, cb));
;     const bf16x8 qf = d0 < 8 ? qr[d0 < 8 ? d0 : 0] : *reinterpret_cast<const bf16x8*>(qx + (d0 - 8) * 1024);
;     p0 = __builtin_amdgcn_mfma_f32_32x32x16_bf16(b0, qf, p0, 0, 0, 0);
;     p1 = __builtin_amdgcn_mfma_f32_32x32x16_bf16(b1, qf, p1, 0, 0, 0); }
	v_mfma_f32_32x32x16_bf16 v[16:31], v[146:149], v[194:197], v[16:31]
	ds_read_b64_tr_b16 v[194:195], v161 offset:0x1600
	ds_read_b64_tr_b16 v[196:197], v161 offset:0x1e00
	s_waitcnt lgkmcnt(6)
	v_mfma_f32_32x32x16_bf16 v[16:31], v[150:153], v[198:201], v[16:31]
	ds_read_b64_tr_b16 v[198:199], v161 offset:0x2600
	ds_read_b64_tr_b16 v[200:201], v161 offset:0x2e00
	s_waitcnt lgkmcnt(6)
	v_mfma_f32_32x32x16_bf16 v[16:31], v[154:157], v[202:205], v[16:31]
	ds_read_b64_tr_b16 v[202:203], v161 offset:0x3600
	ds_read_b64_tr_b16 v[204:205], v161 offset:0x3e00
	s_waitcnt lgkmcnt(6)
	v_mfma_f32_32x32x16_bf16 v[0:15], v[142:145], v[190:193], v[0:15]
	s_waitcnt lgkmcnt(4)
	v_mfma_f32_32x32x16_bf16 v[0:15], v[146:149], v[194:197], v[0:15]
	s_waitcnt lgkmcnt(2)
	v_mfma_f32_32x32x16_bf16 v[0:15], v[150:153], v[198:201], v[0:15]
	s_waitcnt lgkmcnt(0)
	v_mfma_f32_32x32x16_bf16 v[0:15], v[154:157], v[202:205], v[0:15]
	ds_read_b128 v[64:67], v174 offset:49152
	ds_read_b128 v[68:71], v174 offset:61440
	ds_read_b128 v[208:211], v166 offset:49152
	ds_read_b128 v[212:215], v166 offset:61440
	ds_read_b128 v[176:179], v162 offset:49152
	ds_read_b128 v[180:183], v162 offset:61440
	s_waitcnt lgkmcnt(4)
	v_mfma_f32_32x32x16_bf16 v[80:95], v[64:67], v[96:99], 0
	v_mfma_f32_32x32x16_bf16 v[64:79], v[68:71], v[96:99], 0
	s_waitcnt lgkmcnt(2)
	v_mfma_f32_32x32x16_bf16 v[64:79], v[212:215], v[100:103], v[64:79]
	v_mfma_f32_32x32x16_bf16 v[80:95], v[208:211], v[100:103], v[80:95]
	ds_read_b128 v[208:211], v163 offset:49152
	ds_read_b128 v[212:215], v163 offset:61440
	s_waitcnt lgkmcnt(2)
	v_mfma_f32_32x32x16_bf16 v[64:79], v[180:183], v[104:107], v[64:79]
	v_mfma_f32_32x32x16_bf16 v[80:95], v[176:179], v[104:107], v[80:95]
	ds_read_b128 v[176:179], v164 offset:49152
	ds_read_b128 v[180:183], v164 offset:61440
	s_waitcnt lgkmcnt(2)
	v_mfma_f32_32x32x16_bf16 v[64:79], v[212:215], v[108:111], v[64:79]
	v_mfma_f32_32x32x16_bf16 v[80:95], v[208:211], v[108:111], v[80:95]
	ds_read_b128 v[208:211], v165 offset:49152
	ds_read_b128 v[212:215], v165 offset:61440
	s_waitcnt lgkmcnt(2)
	v_mfma_f32_32x32x16_bf16 v[64:79], v[180:183], v[112:115], v[64:79]
	v_mfma_f32_32x32x16_bf16 v[80:95], v[176:179], v[112:115], v[80:95]
	ds_read_b128 v[176:179], v167 offset:49152
	ds_read_b128 v[180:183], v167 offset:61440
	s_waitcnt lgkmcnt(2)
	v_mfma_f32_32x32x16_bf16 v[64:79], v[212:215], v[116:119], v[64:79]
	v_mfma_f32_32x32x16_bf16 v[80:95], v[208:211], v[116:119], v[80:95]
	ds_read_b128 v[208:211], v168 offset:49152
	ds_read_b128 v[212:215], v168 offset:61440
	s_waitcnt lgkmcnt(2)
	v_mfma_f32_32x32x16_bf16 v[64:79], v[180:183], v[120:123], v[64:79]
	v_mfma_f32_32x32x16_bf16 v[80:95], v[176:179], v[120:123], v[80:95]
	ds_read_b128 v[176:179], v169 offset:49152
	ds_read_b128 v[180:183], v169 offset:61440
	ds_read_b128 v[184:187], v173
	s_waitcnt lgkmcnt(3)
	v_mfma_f32_32x32x16_bf16 v[64:79], v[212:215], v[124:127], v[64:79]
	v_mfma_f32_32x32x16_bf16 v[80:95], v[208:211], v[124:127], v[80:95]
	ds_read_b128 v[208:211], v170 offset:49152
	ds_read_b128 v[212:215], v170 offset:61440
	ds_read_b128 v[216:219], v173 offset:1024
	s_waitcnt lgkmcnt(3)
	v_mfma_f32_32x32x16_bf16 v[64:79], v[180:183], v[184:187], v[64:79]
	v_mfma_f32_32x32x16_bf16 v[80:95], v[176:179], v[184:187], v[80:95]
	ds_read_b128 v[176:179], v171 offset:49152
	ds_read_b128 v[180:183], v171 offset:61440
	ds_read_b128 v[184:187], v173 offset:2048
	s_waitcnt lgkmcnt(3)
	v_mfma_f32_32x32x16_bf16 v[64:79], v[212:215], v[216:219], v[64:79]
	v_mfma_f32_32x32x16_bf16 v[80:95], v[208:211], v[216:219], v[80:95]
	ds_read_b128 v[208:211], v172 offset:49152
	ds_read_b128 v[212:215], v172 offset:61440
	ds_read_b128 v[216:219], v173 offset:3072
	s_waitcnt lgkmcnt(3)
	v_mfma_f32_32x32x16_bf16 v[64:79], v[180:183], v[184:187], v[64:79]
	v_mfma_f32_32x32x16_bf16 v[80:95], v[176:179], v[184:187], v[80:95]
	s_waitcnt lgkmcnt(0)
	v_mfma_f32_32x32x16_bf16 v[64:79], v[212:215], v[216:219], v[64:79]
	v_mfma_f32_32x32x16_bf16 v[80:95], v[208:211], v[216:219], v[80:95]
	s_setprio 1
	s_nop 12
	v_max_f32_e32 v142, v81, v81
	v_max_f32_e32 v143, v80, v80
	v_max_f32_e32 v142, v143, v142
	v_max3_f32 v142, v142, v82, v83
	v_max3_f32 v142, v142, v84, v85
	v_max3_f32 v142, v142, v86, v87
	v_max3_f32 v142, v142, v88, v89
	v_max3_f32 v142, v142, v90, v91
	v_max3_f32 v142, v142, v92, v93
	v_max3_f32 v142, v142, v94, v95
	v_max3_f32 v142, v142, v64, v65
	v_max3_f32 v142, v142, v66, v67
	v_max3_f32 v142, v142, v68, v69
	v_max3_f32 v142, v142, v70, v71
	v_max3_f32 v142, v142, v72, v73
	v_max3_f32 v142, v142, v74, v75
	v_max3_f32 v142, v142, v76, v77
	v_max3_f32 v142, v142, v78, v79
	v_mov_b32_e32 v143, v142
	s_nop 1
	v_permlane32_swap_b32_e32 v142, v143
	v_max_f32_e32 v143, v143, v143
	v_max_f32_e32 v142, v142, v142
	v_max_f32_e32 v142, v142, v143
	v_sub_f32_e32 v143, v142, v160
	v_cmp_ge_f32_e32 vcc, s45, v143
	v_max_f32_e32 v143, v160, v160
	v_max_f32_e32 v142, v143, v142
	v_sub_f32_e32 v143, v160, v142
	v_mul_f32_e32 v143, 0x3dd53b94, v143
	v_exp_f32_e32 v143, v143
	s_cmp_eq_u64 vcc, exec
	s_cselect_b64 s[38:39], -1, 0
	v_cndmask_b32_e64 v190, v143, 1.0, s[38:39]
	v_cmp_gt_f32_e32 vcc, 1.0, v190
	s_cbranch_vccz .LattB_321
	s_and_saveexec_b64 s[60:61], s[36:37]
	ds_write_b32 v129, v190 offset:128
	s_or_b64 exec, exec, s[60:61]
	s_waitcnt lgkmcnt(0)
	v_add_u32_e32 v143, s87, v128
	ds_read_b128 v[144:147], v143 offset:224
	ds_read_b128 v[148:151], v143 offset:192
	ds_read_b128 v[152:155], v143 offset:160
	ds_read_b128 v[192:195], v143 offset:128
	s_waitcnt lgkmcnt(0)
	v_pk_mul_f32 v[60:61], v[60:61], v[144:145]
	v_pk_mul_f32 v[56:57], v[56:57], v[148:149]
	v_pk_mul_f32 v[52:53], v[52:53], v[152:153]
	v_pk_mul_f32 v[62:63], v[62:63], v[146:147]
	v_pk_mul_f32 v[58:59], v[58:59], v[150:151]
	v_pk_mul_f32 v[54:55], v[54:55], v[154:155]
	v_pk_mul_f32 v[50:51], v[50:51], v[194:195]
	v_pk_mul_f32 v[48:49], v[48:49], v[192:193]
	v_pk_mul_f32 v[44:45], v[44:45], v[144:145]
	v_pk_mul_f32 v[40:41], v[40:41], v[148:149]
	v_pk_mul_f32 v[36:37], v[36:37], v[152:153]
	v_pk_mul_f32 v[46:47], v[46:47], v[146:147]
	v_pk_mul_f32 v[42:43], v[42:43], v[150:151]
	v_pk_mul_f32 v[38:39], v[38:39], v[154:155]
	v_pk_mul_f32 v[34:35], v[34:35], v[194:195]
	v_pk_mul_f32 v[32:33], v[32:33], v[192:193]
	v_pk_mul_f32 v[28:29], v[28:29], v[144:145]
	v_pk_mul_f32 v[24:25], v[24:25], v[148:149]
	v_pk_mul_f32 v[20:21], v[20:21], v[152:153]
	v_pk_mul_f32 v[30:31], v[30:31], v[146:147]
	v_pk_mul_f32 v[26:27], v[26:27], v[150:151]
	v_pk_mul_f32 v[22:23], v[22:23], v[154:155]
	v_pk_mul_f32 v[18:19], v[18:19], v[194:195]
	v_pk_mul_f32 v[16:17], v[16:17], v[192:193]
	v_pk_mul_f32 v[12:13], v[12:13], v[144:145]
	v_pk_mul_f32 v[8:9], v[8:9], v[148:149]
	v_pk_mul_f32 v[4:5], v[4:5], v[152:153]
	v_pk_mul_f32 v[14:15], v[14:15], v[146:147]
	v_pk_mul_f32 v[10:11], v[10:11], v[150:151]
	v_pk_mul_f32 v[6:7], v[6:7], v[154:155]
	v_pk_mul_f32 v[2:3], v[2:3], v[194:195]
	v_pk_mul_f32 v[0:1], v[0:1], v[192:193]
; __device__ __forceinline__ void partialSM(f32x16& p0, f32x16& p1, float& m_reg, float& mn, float& alpha) {
;     ...
;   const float mnC = -mn * C;
; #pragma unroll
;   for (int r = 0; r < 16; ++r) p0[r] = fmaf(p0[r], C, mnC);
; #pragma unroll
;   for (int r = 0; r < 16; ++r) p1[r] = fmaf(p1[r], C, mnC);
; #pragma unroll
;   for (int r = 0; r < 16; ++r) p0[r] = __builtin_amdgcn_exp2f(p0[r]);
; }
; __device__ __forceinline__ void finishSM(f32x16& p0, f32x16& p1, float alpha, float& l_reg, bf16x8& pa0, bf16x8& pa1, bf16x8& pa2, bf16x8& pa3) {
; #pragma unroll
;   for (int r = 0; r < 16; ++r) p1[r] = __builtin_amdgcn_exp2f(p1[r]);
;   float ps = 0;
; #pragma unroll
;   for (int r = 0; r < 16; ++r) ps += p0[r];
; #pragma unroll
;   for (int r = 0; r < 16; ++r) ps += p1[r];
;   { auto rr = __builtin_amdgcn_permlane32_swap(__float_as_uint(ps), __float_as_uint(ps), false, false);
;     ps = __uint_as_float(rr[0]) + __uint_as_float(rr[1]); }
;   l_reg = l_reg * alpha + ps;
;     ...
;   PK4(p0, 0, pa0); PK4(p0, 8, pa1); PK4(p1, 0, pa2); PK4(p1, 8, pa3);
;     ...
; }
.LattB_321:
	s_ashr_i32 s59, s58, 31
	s_add_i32 s63, s63, 2
	s_cmp_lt_u32 s63, s84
	v_cndmask_b32_e64 v160, v142, v160, s[38:39]
	s_cselect_b32 s38, 0, s84
	s_cselect_b32 s39, s2, s83
	s_lshl_b32 s38, s38, 6
	s_sub_i32 s38, s39, s38
	s_add_i32 s38, s52, s38
	s_add_i32 s38, s38, 64
	s_mul_hi_i32 s39, s38, 0xc00
	s_mulk_i32 s38, 0xc00
	s_add_u32 s38, s30, s38
	v_mul_f32_e32 v142, 0xbdd53b94, v160
	s_waitcnt vmcnt(0)
	s_addc_u32 s39, s31, s39
	v_fmamk_f32 v192, v64, 0x3dd53b94, v142
	v_fmamk_f32 v193, v65, 0x3dd53b94, v142
	s_waitcnt lgkmcnt(0)
	s_barrier
	v_lshl_add_u64 v[64:65], s[38:39], 0, v[132:133]
	s_mov_b32 m0, s94
	v_fmamk_f32 v80, v80, 0x3dd53b94, v142
	global_load_lds_dwordx4 v[64:65], off
	v_lshl_add_u64 v[64:65], s[38:39], 0, v[130:131]
	s_mov_b32 m0, s75
	v_fmamk_f32 v81, v81, 0x3dd53b94, v142
	global_load_lds_dwordx4 v[64:65], off
	v_lshl_add_u64 v[64:65], s[38:39], 0, v[136:137]
	s_mov_b32 m0, s76
	s_lshl_b64 s[38:39], s[58:59], 11
	global_load_lds_dwordx4 v[64:65], off
	v_lshl_add_u64 v[64:65], v[140:141], 0, s[38:39]
	s_mov_b32 m0, s3
	v_fmamk_f32 v82, v82, 0x3dd53b94, v142
	global_load_lds_dwordx4 v[64:65], off
	v_lshl_add_u64 v[64:65], v[64:65], 0, s[22:23]
	s_mov_b32 m0, s29
	v_fmamk_f32 v83, v83, 0x3dd53b94, v142
	global_load_lds_dwordx4 v[64:65], off
	v_fmamk_f32 v84, v84, 0x3dd53b94, v142
	v_fmamk_f32 v85, v85, 0x3dd53b94, v142
	v_fmamk_f32 v86, v86, 0x3dd53b94, v142
	v_fmamk_f32 v87, v87, 0x3dd53b94, v142
	v_fmamk_f32 v88, v88, 0x3dd53b94, v142
	v_fmamk_f32 v89, v89, 0x3dd53b94, v142
	v_fmamk_f32 v90, v90, 0x3dd53b94, v142
	v_fmamk_f32 v91, v91, 0x3dd53b94, v142
	v_fmamk_f32 v92, v92, 0x3dd53b94, v142
	v_fmamk_f32 v93, v93, 0x3dd53b94, v142
	v_fmamk_f32 v94, v94, 0x3dd53b94, v142
	v_fmamk_f32 v95, v95, 0x3dd53b94, v142
	v_fmamk_f32 v194, v66, 0x3dd53b94, v142
	v_fmamk_f32 v195, v67, 0x3dd53b94, v142
	v_fmamk_f32 v196, v68, 0x3dd53b94, v142
	v_fmamk_f32 v197, v69, 0x3dd53b94, v142
	v_fmamk_f32 v198, v70, 0x3dd53b94, v142
	v_fmamk_f32 v199, v71, 0x3dd53b94, v142
	v_fmamk_f32 v200, v72, 0x3dd53b94, v142
	v_fmamk_f32 v201, v73, 0x3dd53b94, v142
	v_fmamk_f32 v202, v74, 0x3dd53b94, v142
	v_fmamk_f32 v203, v75, 0x3dd53b94, v142
	v_fmamk_f32 v204, v76, 0x3dd53b94, v142
	v_fmamk_f32 v205, v77, 0x3dd53b94, v142
	v_fmamk_f32 v206, v78, 0x3dd53b94, v142
	v_fmamk_f32 v207, v79, 0x3dd53b94, v142
	v_exp_f32_e32 v151, v80
	v_exp_f32_e32 v152, v81
	v_exp_f32_e32 v153, v82
	v_exp_f32_e32 v154, v83
	v_exp_f32_e32 v155, v84
	v_exp_f32_e32 v156, v85
	v_exp_f32_e32 v157, v86
	v_exp_f32_e32 v191, v87
	v_exp_f32_e32 v143, v88
	v_exp_f32_e32 v144, v89
	v_exp_f32_e32 v145, v90
	v_exp_f32_e32 v146, v91
	v_exp_f32_e32 v147, v92
	v_exp_f32_e32 v148, v93
	v_exp_f32_e32 v149, v94
	v_exp_f32_e32 v150, v95
	v_add_f32_e32 v220, 0, v151
	v_add_f32_e32 v220, v152, v220
	v_add_f32_e32 v220, v153, v220
	v_add_f32_e32 v220, v154, v220
	v_add_f32_e32 v220, v155, v220
	v_add_f32_e32 v220, v156, v220
	v_add_f32_e32 v220, v157, v220
	v_add_f32_e32 v220, v191, v220
	v_add_f32_e32 v220, v143, v220
	v_add_f32_e32 v220, v144, v220
	v_add_f32_e32 v220, v145, v220
	v_add_f32_e32 v220, v146, v220
	v_exp_f32_e32 v88, v192
	v_add_f32_e32 v220, v147, v220
	v_exp_f32_e32 v91, v193
	v_add_f32_e32 v220, v148, v220
	v_exp_f32_e32 v192, v194
	v_add_f32_e32 v220, v149, v220
	v_exp_f32_e32 v193, v195
	v_add_f32_e32 v220, v150, v220
	v_exp_f32_e32 v194, v196
	v_add_f32_e32 v220, v88, v220
	v_exp_f32_e32 v195, v197
	v_add_f32_e32 v220, v91, v220
	v_exp_f32_e32 v196, v198
	v_add_f32_e32 v220, v192, v220
	v_exp_f32_e32 v197, v199
	v_add_f32_e32 v220, v193, v220
	v_exp_f32_e32 v198, v200
	v_add_f32_e32 v220, v194, v220
	v_exp_f32_e32 v199, v201
	v_add_f32_e32 v220, v195, v220
	v_exp_f32_e32 v200, v202
	v_add_f32_e32 v220, v196, v220
	v_exp_f32_e32 v201, v203
	v_add_f32_e32 v220, v197, v220
	v_exp_f32_e32 v202, v204
	v_add_f32_e32 v220, v198, v220
	v_exp_f32_e32 v203, v205
	v_add_f32_e32 v220, v199, v220
	v_exp_f32_e32 v204, v206
	v_add_f32_e32 v220, v200, v220
	v_exp_f32_e32 v205, v207
	v_add_f32_e32 v220, v201, v220
	v_add_f32_e32 v220, v202, v220
	v_add_f32_e32 v220, v203, v220
	v_add_f32_e32 v220, v204, v220
	v_add_f32_e32 v220, v205, v220
	v_mov_b32_e32 v221, v220
	s_nop 1
	v_permlane32_swap_b32_e32 v220, v221
	v_cvt_pk_bf16_f32 v92, v151, v152
	v_cvt_pk_bf16_f32 v93, v153, v154
	v_cvt_pk_bf16_f32 v94, v155, v156
	v_cvt_pk_bf16_f32 v95, v157, v191
	v_cvt_pk_bf16_f32 v144, v143, v144
	v_cvt_pk_bf16_f32 v145, v145, v146
	v_cvt_pk_bf16_f32 v146, v147, v148
	v_cvt_pk_bf16_f32 v147, v149, v150
	v_cvt_pk_bf16_f32 v148, v88, v91
	v_cvt_pk_bf16_f32 v149, v192, v193
	v_cvt_pk_bf16_f32 v150, v194, v195
	v_cvt_pk_bf16_f32 v151, v196, v197
	v_cvt_pk_bf16_f32 v152, v198, v199
	v_cvt_pk_bf16_f32 v153, v200, v201
	v_cvt_pk_bf16_f32 v154, v202, v203
	v_cvt_pk_bf16_f32 v155, v204, v205
	v_permlane32_swap_b32_e32 v92, v94
	v_permlane32_swap_b32_e32 v93, v95
	v_permlane32_swap_b32_e32 v144, v146
	v_permlane32_swap_b32_e32 v145, v147
	v_permlane32_swap_b32_e32 v148, v150
	v_permlane32_swap_b32_e32 v149, v151
	v_permlane32_swap_b32_e32 v152, v154
	v_permlane32_swap_b32_e32 v153, v155
	s_setprio 0
	ds_read_b64_tr_b16 v[192:193], v159 offset:0
	ds_read_b64_tr_b16 v[194:195], v159 offset:0x800
	ds_read_b64_tr_b16 v[196:197], v159 offset:0x1000
	ds_read_b64_tr_b16 v[198:199], v159 offset:0x1800
	ds_read_b64_tr_b16 v[200:201], v159 offset:0x2000
	ds_read_b64_tr_b16 v[202:203], v159 offset:0x2800
	ds_read_b64_tr_b16 v[204:205], v159 offset:0x3000
	ds_read_b64_tr_b16 v[206:207], v159 offset:0x3800
	s_waitcnt lgkmcnt(6)
; #define SBAR() __builtin_amdgcn_sched_barrier(0)
; __device__ __forceinline__ void qkt(f32x16& p0, f32x16& p1, const char* Ks, const bf16x8* qr, const char* qx, int r32, int hi, int mode) {
;   p0 = f32x16{}; p1 = f32x16{};
; #pragma unroll
;   for (int d0 = 0; d0 < 12; ++d0) { const int cb = (d0 * 16 + hi * 8) * 2;
;     bf16x8 b0 = *reinterpret_cast<const bf16x8*>(Ks + KSWZ(r32, cb));
;     bf16x8 b1 = *reinterpret_cast<const bf16x8*>(Ks + KSWZ(32 + r32, cb));
;     const bf16x8 qf = d0 < 8 ? qr[d0 < 8 ? d0 : 0] : *reinterpret_cast<const bf16x8*>(qx + (d0 - 8) * 1024);
;     p0 = __builtin_amdgcn_mfma_f32_32x32x16_bf16(b0, qf, p0, 0, 0, 0);
;     p1 = __builtin_amdgcn_mfma_f32_32x32x16_bf16(b1, qf, p1, 0, 0, 0); }
; template <int D0> __device__ __forceinline__ void pv_one(f32x16& od, int vb, bf16x8 pa0, bf16x8 pa1, bf16x8 pa2, bf16x8 pa3) {
;   const s16x4 l0 = tr_read<v_rd_off(D0, 0, 0)>(vb), h0 = tr_read<v_rd_off(D0, 0, 1)>(vb), l1 = tr_read<v_rd_off(D0, 1, 0)>(vb), h1 = tr_read<v_rd_off(D0, 1, 1)>(vb);
;   const s16x4 l2 = tr_read<v_rd_off(D0, 2, 0)>(vb), h2 = tr_read<v_rd_off(D0, 2, 1)>(vb), l3 = tr_read<v_rd_off(D0, 3, 0)>(vb), h3 = tr_read<v_rd_off(D0, 3, 1)>(vb);
;   asm volatile("s_waitcnt lgkmcnt(0)" ::: "memory"); SBAR();
;     ...
;   od = __builtin_amdgcn_mfma_f32_32x32x16_bf16(pa0, PK(l0, h0), od, 0, 0, 0);
;   od = __builtin_amdgcn_mfma_f32_32x32x16_bf16(pa1, PK(l1, h1), od, 0, 0, 0);
;   od = __builtin_amdgcn_mfma_f32_32x32x16_bf16(pa2, PK(l2, h2), od, 0, 0, 0);
;   od = __builtin_amdgcn_mfma_f32_32x32x16_bf16(pa3, PK(l3, h3), od, 0, 0, 0);
;     ...
; }
; __device__ __forceinline__ void pv_d0(f32x16* o, int vb, bf16x8 pa0, bf16x8 pa1, bf16x8 pa2, bf16x8 pa3) {
;   pv_one<0>(o[0], vb, pa0, pa1, pa2, pa3); pv_one<1>(o[1], vb, pa0, pa1, pa2, pa3); pv_one<2>(o[2], vb, pa0, pa1, pa2, pa3); pv_one<3>(o[3], vb, pa0, pa1, pa2, pa3);
	s_nop 0
	v_mfma_f32_32x32x16_bf16 v[48:63], v[92:95], v[192:195], v[48:63]
	ds_read_b64_tr_b16 v[192:193], v159 offset:0x200
	ds_read_b64_tr_b16 v[194:195], v159 offset:0xa00
	s_waitcnt lgkmcnt(6)
	v_mfma_f32_32x32x16_bf16 v[48:63], v[144:147], v[196:199], v[48:63]
	ds_read_b64_tr_b16 v[196:197], v159 offset:0x1200
	ds_read_b64_tr_b16 v[198:199], v159 offset:0x1a00
	s_waitcnt lgkmcnt(6)
	v_mfma_f32_32x32x16_bf16 v[48:63], v[148:151], v[200:203], v[48:63]
	ds_read_b64_tr_b16 v[200:201], v159 offset:0x2200
	ds_read_b64_tr_b16 v[202:203], v159 offset:0x2a00
	s_waitcnt lgkmcnt(6)
	v_mfma_f32_32x32x16_bf16 v[48:63], v[152:155], v[204:207], v[48:63]
	ds_read_b64_tr_b16 v[204:205], v159 offset:0x3200
	ds_read_b64_tr_b16 v[206:207], v159 offset:0x3a00
	s_waitcnt lgkmcnt(6)
	v_mfma_f32_32x32x16_bf16 v[32:47], v[92:95], v[192:195], v[32:47]
	ds_read_b64_tr_b16 v[192:193], v159 offset:0x400
	ds_read_b64_tr_b16 v[194:195], v159 offset:0xc00
	s_waitcnt lgkmcnt(6)
	v_mfma_f32_32x32x16_bf16 v[32:47], v[144:147], v[196:199], v[32:47]
	ds_read_b64_tr_b16 v[196:197], v159 offset:0x1400
	ds_read_b64_tr_b16 v[198:199], v159 offset:0x1c00
	s_waitcnt lgkmcnt(6)
	v_mfma_f32_32x32x16_bf16 v[32:47], v[148:151], v[200:203], v[32:47]
	ds_read_b64_tr_b16 v[200:201], v159 offset:0x2400
	ds_read_b64_tr_b16 v[202:203], v159 offset:0x2c00
	s_waitcnt lgkmcnt(6)
	v_mfma_f32_32x32x16_bf16 v[32:47], v[152:155], v[204:207], v[32:47]
	ds_read_b64_tr_b16 v[204:205], v159 offset:0x3400
	ds_read_b64_tr_b16 v[206:207], v159 offset:0x3c00
	s_waitcnt lgkmcnt(6)
	v_mfma_f32_32x32x16_bf16 v[16:31], v[92:95], v[192:195], v[16:31]
	ds_read_b64_tr_b16 v[192:193], v159 offset:0x600
	ds_read_b64_tr_b16 v[194:195], v159 offset:0xe00
	s_waitcnt lgkmcnt(6)
	v_mfma_f32_32x32x16_bf16 v[16:31], v[144:147], v[196:199], v[16:31]
	ds_read_b64_tr_b16 v[196:197], v159 offset:0x1600
	ds_read_b64_tr_b16 v[198:199], v159 offset:0x1e00
	s_waitcnt lgkmcnt(6)
	v_mfma_f32_32x32x16_bf16 v[16:31], v[148:151], v[200:203], v[16:31]
	ds_read_b64_tr_b16 v[200:201], v159 offset:0x2600
	ds_read_b64_tr_b16 v[202:203], v159 offset:0x2e00
	s_waitcnt lgkmcnt(6)
	v_mfma_f32_32x32x16_bf16 v[16:31], v[152:155], v[204:207], v[16:31]
	ds_read_b64_tr_b16 v[204:205], v159 offset:0x3600
	ds_read_b64_tr_b16 v[206:207], v159 offset:0x3e00
	s_waitcnt lgkmcnt(6)
	v_mfma_f32_32x32x16_bf16 v[0:15], v[92:95], v[192:195], v[0:15]
	s_waitcnt lgkmcnt(4)
	v_mfma_f32_32x32x16_bf16 v[0:15], v[144:147], v[196:199], v[0:15]
	s_waitcnt lgkmcnt(2)
	v_mfma_f32_32x32x16_bf16 v[0:15], v[148:151], v[200:203], v[0:15]
	s_waitcnt lgkmcnt(0)
	v_mfma_f32_32x32x16_bf16 v[0:15], v[152:155], v[204:207], v[0:15]
	ds_read_b128 v[64:67], v174 offset:24576
	ds_read_b128 v[80:83], v174 offset:36864
	ds_read_b128 v[208:211], v166 offset:24576
	ds_read_b128 v[212:215], v166 offset:36864
	ds_read_b128 v[176:179], v162 offset:24576
	ds_read_b128 v[180:183], v162 offset:36864
	s_cmp_eq_u32 s12, s84
	s_cselect_b64 vcc, -1, 0
	s_waitcnt lgkmcnt(4)
	v_mfma_f32_32x32x16_bf16 v[64:79], v[64:67], v[96:99], 0
	v_mfma_f32_32x32x16_bf16 v[80:95], v[80:83], v[96:99], 0
	s_waitcnt lgkmcnt(2)
	v_mfma_f32_32x32x16_bf16 v[64:79], v[208:211], v[100:103], v[64:79]
	v_mfma_f32_32x32x16_bf16 v[80:95], v[212:215], v[100:103], v[80:95]
	ds_read_b128 v[208:211], v163 offset:24576
	ds_read_b128 v[212:215], v163 offset:36864
	s_waitcnt lgkmcnt(2)
	v_mfma_f32_32x32x16_bf16 v[64:79], v[176:179], v[104:107], v[64:79]
	v_mfma_f32_32x32x16_bf16 v[80:95], v[180:183], v[104:107], v[80:95]
	ds_read_b128 v[176:179], v164 offset:24576
	ds_read_b128 v[180:183], v164 offset:36864
	s_waitcnt lgkmcnt(2)
	v_mfma_f32_32x32x16_bf16 v[64:79], v[208:211], v[108:111], v[64:79]
	v_mfma_f32_32x32x16_bf16 v[80:95], v[212:215], v[108:111], v[80:95]
	ds_read_b128 v[208:211], v165 offset:24576
	ds_read_b128 v[212:215], v165 offset:36864
	s_waitcnt lgkmcnt(2)
; __device__ __forceinline__ void partialSM(f32x16& p0, f32x16& p1, float& m_reg, float& mn, float& alpha) {
;   constexpr float C = ATT_SCALE * 1.4426950408889634f;
;   float pmax = p0[0];
; #pragma unroll
;   for (int r = 1; r < 16; ++r) pmax = fmaxf(pmax, p0[r]);
; #pragma unroll
;   for (int r = 0; r < 16; ++r) pmax = fmaxf(pmax, p1[r]);
;   { auto rr = __builtin_amdgcn_permlane32_swap(__float_as_uint(pmax), __float_as_uint(pmax), false, false);
;     pmax = fmaxf(__uint_as_float(rr[0]), __uint_as_float(rr[1])); }
;   if (__builtin_expect(__all(pmax - m_reg <= ATT_THR / ATT_SCALE), 1)) { mn = m_reg; alpha = 1.f; }
;   else { mn = fmaxf(m_reg, pmax); alpha = __builtin_amdgcn_exp2f((m_reg - mn) * C); m_reg = mn; }
; __device__ __forceinline__ void qkt(f32x16& p0, f32x16& p1, const char* Ks, const bf16x8* qr, const char* qx, int r32, int hi, int mode) {
;     ...
;   if (mode != 0) {
;     constexpr float NEG = -1e30f;
; #pragma unroll
;     for (int r = 0; r < 16; ++r) p1[r] = NEG;
; #pragma unroll
;     for (int r = 8; r < 16; ++r) p0[r] = NEG;
;     if (mode == 2) {
; #pragma unroll
;       for (int r = 0; r < 8; ++r) p0[r] = NEG; }
;   }
	v_mfma_f32_32x32x16_bf16 v[64:79], v[176:179], v[112:115], v[64:79]
	v_mfma_f32_32x32x16_bf16 v[80:95], v[180:183], v[112:115], v[80:95]
	ds_read_b128 v[176:179], v167 offset:24576
	ds_read_b128 v[180:183], v167 offset:36864
	s_waitcnt lgkmcnt(2)
	v_mfma_f32_32x32x16_bf16 v[64:79], v[208:211], v[116:119], v[64:79]
	v_mfma_f32_32x32x16_bf16 v[80:95], v[212:215], v[116:119], v[80:95]
	ds_read_b128 v[208:211], v168 offset:24576
	ds_read_b128 v[212:215], v168 offset:36864
	s_waitcnt lgkmcnt(2)
	v_mfma_f32_32x32x16_bf16 v[64:79], v[176:179], v[120:123], v[64:79]
	v_mfma_f32_32x32x16_bf16 v[80:95], v[180:183], v[120:123], v[80:95]
	ds_read_b128 v[176:179], v169 offset:24576
	ds_read_b128 v[180:183], v169 offset:36864
	ds_read_b128 v[184:187], v173
	s_waitcnt lgkmcnt(3)
	v_mfma_f32_32x32x16_bf16 v[64:79], v[208:211], v[124:127], v[64:79]
	v_mfma_f32_32x32x16_bf16 v[80:95], v[212:215], v[124:127], v[80:95]
	ds_read_b128 v[208:211], v170 offset:24576
	ds_read_b128 v[212:215], v170 offset:36864
	ds_read_b128 v[216:219], v173 offset:1024
	s_waitcnt lgkmcnt(3)
	v_mfma_f32_32x32x16_bf16 v[64:79], v[176:179], v[184:187], v[64:79]
	v_mfma_f32_32x32x16_bf16 v[80:95], v[180:183], v[184:187], v[80:95]
	ds_read_b128 v[176:179], v171 offset:24576
	ds_read_b128 v[180:183], v171 offset:36864
	ds_read_b128 v[184:187], v173 offset:2048
	s_waitcnt lgkmcnt(3)
	v_mfma_f32_32x32x16_bf16 v[64:79], v[208:211], v[216:219], v[64:79]
	v_mfma_f32_32x32x16_bf16 v[80:95], v[212:215], v[216:219], v[80:95]
	ds_read_b128 v[208:211], v172 offset:24576
	ds_read_b128 v[212:215], v172 offset:36864
	ds_read_b128 v[216:219], v173 offset:3072
	s_waitcnt lgkmcnt(3)
	v_mfma_f32_32x32x16_bf16 v[64:79], v[176:179], v[184:187], v[64:79]
	v_mfma_f32_32x32x16_bf16 v[80:95], v[180:183], v[184:187], v[80:95]
	s_waitcnt lgkmcnt(0)
	v_mfma_f32_32x32x16_bf16 v[64:79], v[208:211], v[216:219], v[64:79]
	v_mfma_f32_32x32x16_bf16 v[80:95], v[212:215], v[216:219], v[80:95]
	s_setprio 1
	s_nop 10
	v_cndmask_b32_e32 v208, v79, v229, vcc
	v_cndmask_b32_e32 v209, v78, v229, vcc
	v_cndmask_b32_e32 v210, v77, v229, vcc
	v_cndmask_b32_e32 v211, v76, v229, vcc
	v_cndmask_b32_e32 v212, v75, v229, vcc
	v_cndmask_b32_e32 v213, v74, v229, vcc
	v_cndmask_b32_e32 v214, v73, v229, vcc
	v_cndmask_b32_e32 v79, v89, v229, vcc
	v_cndmask_b32_e32 v78, v88, v229, vcc
	v_cndmask_b32_e32 v77, v91, v229, vcc
	v_cndmask_b32_e32 v76, v90, v229, vcc
	v_cndmask_b32_e32 v215, v72, v229, vcc
	v_cndmask_b32_e32 v73, v95, v229, vcc
	v_cndmask_b32_e32 v72, v94, v229, vcc
	v_cndmask_b32_e32 v75, v93, v229, vcc
	v_cndmask_b32_e32 v74, v92, v229, vcc
	v_cndmask_b32_e32 v87, v87, v229, vcc
	v_cndmask_b32_e32 v86, v86, v229, vcc
	v_cndmask_b32_e32 v85, v85, v229, vcc
	v_cndmask_b32_e32 v84, v84, v229, vcc
	v_cndmask_b32_e32 v83, v83, v229, vcc
	v_cndmask_b32_e32 v82, v82, v229, vcc
	v_cndmask_b32_e32 v81, v81, v229, vcc
	v_cndmask_b32_e32 v80, v80, v229, vcc
	v_max_f32_e32 v88, v65, v65
	v_max_f32_e32 v91, v64, v64
	v_max_f32_e32 v88, v91, v88
	v_max3_f32 v88, v88, v66, v67
	v_max3_f32 v88, v88, v68, v69
	v_max3_f32 v88, v88, v70, v71
	v_max3_f32 v88, v88, v215, v214
	v_max3_f32 v88, v88, v213, v212
	v_max3_f32 v88, v88, v211, v210
	v_max3_f32 v88, v88, v209, v208
	v_max3_f32 v88, v88, v80, v81
	v_max3_f32 v88, v88, v82, v83
	v_max3_f32 v88, v88, v84, v85
	v_max3_f32 v88, v88, v86, v87
	v_max3_f32 v88, v88, v78, v79
	v_max3_f32 v88, v88, v76, v77
	v_max3_f32 v88, v88, v74, v75
	v_max3_f32 v88, v88, v72, v73
	v_mov_b32_e32 v91, v88
	s_nop 1
	v_permlane32_swap_b32_e32 v88, v91
	v_max_f32_e32 v91, v91, v91
	v_max_f32_e32 v88, v88, v88
	v_max_f32_e32 v91, v88, v91
	v_sub_f32_e32 v88, v91, v160
	v_cmp_ge_f32_e32 vcc, s45, v88
	v_mov_b32_e32 v88, 1.0
	s_cmp_eq_u64 vcc, exec
	s_cbranch_scc0 .LattB_328
	v_cmp_gt_f32_e32 vcc, 1.0, v88
	s_cbranch_vccz .LattB_326

; #define SBAR() __builtin_amdgcn_sched_barrier(0)
; #define RESC(a) do { if (__any((a) < 1.f)) { if (hi == 0) al_l[r32] = (a); asm volatile("s_waitcnt lgkmcnt(0)" ::: "memory"); \
;     for (int d = 0; d < 4; ++d) for (int r = 0; r < 16; ++r) o[d][r] *= al_l[crow(r, hi)]; } } while (0)
; #define ISSUE_V(j, stg) do { const long _k0 = TROW(j); const char* _vt = (const char*)Vh + _k0 * (LDV * 2); _Pragma("unroll") for (int _i = 0; _i < 2; ++_i) \
;     __builtin_amdgcn_global_load_lds((const unsigned*)(_vt + ovv[_i]), (LAS unsigned*)(ldsL + (stg) * SHM_V + (wid * 2 + _i) * 1024), 16, 0, 0); } while (0)
; #define WAITV(n) asm volatile("s_waitcnt vmcnt(" #n ")" ::: "memory")
; #define ABAR() do { asm volatile("s_waitcnt lgkmcnt(0)" ::: "memory"); __builtin_amdgcn_s_barrier(); asm volatile("" ::: "memory"); } while (0)
; #define RESC(a) do { if (__any((a) < 1.f)) { if (hi == 0) al_l[r32] = (a); asm volatile("s_waitcnt lgkmcnt(0)" ::: "memory"); \
;     for (int d = 0; d < 4; ++d) for (int r = 0; r < 16; ++r) o[d][r] *= al_l[crow(r, hi)]; } } while (0)
; __device__ __forceinline__ void finishSM(f32x16& p0, f32x16& p1, float alpha, float& l_reg, bf16x8& pa0, bf16x8& pa1, bf16x8& pa2, bf16x8& pa3) {
; #pragma unroll
;   for (int r = 0; r < 16; ++r) p1[r] = __builtin_amdgcn_exp2f(p1[r]);
;   float ps = 0;
; #pragma unroll
;   for (int r = 0; r < 16; ++r) ps += p0[r];
; #pragma unroll
;   for (int r = 0; r < 16; ++r) ps += p1[r];
;   { auto rr = __builtin_amdgcn_permlane32_swap(__float_as_uint(ps), __float_as_uint(ps), false, false);
;     ps = __uint_as_float(rr[0]) + __uint_as_float(rr[1]); }
;   l_reg = l_reg * alpha + ps;
;     ...
;   PK4(p0, 0, pa0); PK4(p0, 8, pa1); PK4(p1, 0, pa2); PK4(p1, 8, pa3);
;     ...
; }
; __device__ __forceinline__ void attn_body2(const bf16_t* __restrict__ Qb, const bf16_t* __restrict__ Kh, const bf16_t* __restrict__ Vh, ...
;     ...
;   ISSUE_V(NT - 1, 1);
;   SBAR(); qkt(pB0, pB1, K_lds + SHM_K, qr, qx, r32, hi, 2);
;   finishSM(pA0, pA1, alA, l_reg, pa0, pa1, pa2, pa3); SBAR();
;   pv_d0(o, vb0, pa0, pa1, pa2, pa3); partialSM(pB0, pB1, m_reg, mnB, alB);
;   WAITV(0); ABAR(); RESC(alB);
.LBB0_329:
	s_setprio 0
	s_ashr_i32 s29, s28, 31
	s_lshl_b64 s[2:3], s[28:29], 11
	s_add_u32 s2, s26, s2
	s_addc_u32 s3, s27, s3
	v_lshl_add_u64 v[64:65], s[2:3], 0, v[138:139]
	s_mov_b64 s[2:3], 0x2020000
	s_mov_b32 m0, s62
	v_lshl_add_u64 v[66:67], v[64:65], 0, s[2:3]
	s_mov_b64 s[2:3], 0x2020080
	global_load_lds_dwordx4 v[66:67], off
	v_lshl_add_u64 v[64:65], v[64:65], 0, s[2:3]
	s_mov_b32 m0, s56
	s_nop 0
	global_load_lds_dwordx4 v[64:65], off
	v_add_f32_e32 v64, 0, v199
	v_add_f32_e32 v64, v200, v64
	v_add_f32_e32 v64, v201, v64
	v_add_f32_e32 v64, v203, v64
	v_add_f32_e32 v64, v204, v64
	v_add_f32_e32 v64, v206, v64
	v_add_f32_e32 v64, v202, v64
	v_add_f32_e32 v64, v205, v64
	v_add_f32_e32 v64, v191, v64
	v_add_f32_e32 v64, v193, v64
	v_add_f32_e32 v64, v194, v64
	v_add_f32_e32 v64, v197, v64
	v_exp_f32_e32 v74, v156
	v_add_f32_e32 v64, v192, v64
	v_exp_f32_e32 v75, v157
	v_add_f32_e32 v64, v195, v64
	v_exp_f32_e32 v76, v154
	v_add_f32_e32 v64, v196, v64
	v_exp_f32_e32 v77, v155
	v_add_f32_e32 v64, v198, v64
	v_exp_f32_e32 v78, v152
	v_add_f32_e32 v64, v74, v64
	v_exp_f32_e32 v79, v153
	v_add_f32_e32 v64, v75, v64
	v_exp_f32_e32 v80, v150
	v_add_f32_e32 v64, v76, v64
	v_exp_f32_e32 v81, v151
	v_add_f32_e32 v64, v77, v64
	v_exp_f32_e32 v82, v148
	v_add_f32_e32 v64, v78, v64
	v_exp_f32_e32 v83, v149
	v_add_f32_e32 v64, v79, v64
	v_exp_f32_e32 v84, v146
	v_add_f32_e32 v64, v80, v64
	v_exp_f32_e32 v85, v147
	v_add_f32_e32 v64, v81, v64
	v_exp_f32_e32 v86, v144
	v_add_f32_e32 v64, v82, v64
	v_exp_f32_e32 v87, v145
	v_add_f32_e32 v64, v83, v64
	v_exp_f32_e32 v89, v142
	v_add_f32_e32 v64, v84, v64
	v_exp_f32_e32 v90, v143
	v_add_f32_e32 v64, v85, v64
	v_add_f32_e32 v64, v86, v64
	v_add_f32_e32 v64, v87, v64
	v_add_f32_e32 v64, v89, v64
	v_add_f32_e32 v64, v90, v64
	v_mov_b32_e32 v65, v64
	v_cvt_pk_bf16_f32 v66, v199, v200
	v_cvt_pk_bf16_f32 v67, v201, v203
	v_cvt_pk_bf16_f32 v68, v204, v206
	v_cvt_pk_bf16_f32 v69, v202, v205
	v_permlane32_swap_b32_e32 v64, v65
	v_permlane32_swap_b32_e32 v66, v68
	v_permlane32_swap_b32_e32 v67, v69
	v_cvt_pk_bf16_f32 v70, v191, v193
	v_cvt_pk_bf16_f32 v71, v194, v197
	v_cvt_pk_bf16_f32 v72, v192, v195
	v_cvt_pk_bf16_f32 v73, v196, v198
	v_cvt_pk_bf16_f32 v74, v74, v75
	v_cvt_pk_bf16_f32 v75, v76, v77
	v_cvt_pk_bf16_f32 v76, v78, v79
	v_cvt_pk_bf16_f32 v77, v80, v81
	v_cvt_pk_bf16_f32 v78, v82, v83
	v_cvt_pk_bf16_f32 v79, v84, v85
	v_cvt_pk_bf16_f32 v80, v86, v87
	v_cvt_pk_bf16_f32 v81, v89, v90
	v_permlane32_swap_b32_e32 v70, v72
	v_permlane32_swap_b32_e32 v71, v73
	v_permlane32_swap_b32_e32 v74, v76
	v_permlane32_swap_b32_e32 v75, v77
	v_permlane32_swap_b32_e32 v78, v80
	v_permlane32_swap_b32_e32 v79, v81
	ds_read_b64_tr_b16 v[82:83], v161 offset:0
	ds_read_b64_tr_b16 v[84:85], v161 offset:0x800
	ds_read_b64_tr_b16 v[90:91], v161 offset:0x1000
	ds_read_b64_tr_b16 v[92:93], v161 offset:0x1800
	ds_read_b64_tr_b16 v[94:95], v161 offset:0x2000
	ds_read_b64_tr_b16 v[96:97], v161 offset:0x2800
	ds_read_b64_tr_b16 v[98:99], v161 offset:0x3000
	ds_read_b64_tr_b16 v[100:101], v161 offset:0x3800
	s_waitcnt lgkmcnt(0)
	s_nop 0
	v_mfma_f32_32x32x16_bf16 v[48:63], v[66:69], v[82:85], v[48:63]
	ds_read_b64_tr_b16 v[82:83], v161 offset:0x200
	ds_read_b64_tr_b16 v[84:85], v161 offset:0xa00
	v_mfma_f32_32x32x16_bf16 v[48:63], v[70:73], v[90:93], v[48:63]
	ds_read_b64_tr_b16 v[90:91], v161 offset:0x1200
	ds_read_b64_tr_b16 v[92:93], v161 offset:0x1a00
	v_mfma_f32_32x32x16_bf16 v[48:63], v[74:77], v[94:97], v[48:63]
	ds_read_b64_tr_b16 v[94:95], v161 offset:0x2200
	ds_read_b64_tr_b16 v[96:97], v161 offset:0x2a00
	v_mfma_f32_32x32x16_bf16 v[48:63], v[78:81], v[98:101], v[48:63]
	ds_read_b64_tr_b16 v[98:99], v161 offset:0x3200
	ds_read_b64_tr_b16 v[100:101], v161 offset:0x3a00
	s_waitcnt lgkmcnt(0)
	v_mfma_f32_32x32x16_bf16 v[32:47], v[66:69], v[82:85], v[32:47]
	ds_read_b64_tr_b16 v[82:83], v161 offset:0x400
	ds_read_b64_tr_b16 v[84:85], v161 offset:0xc00
	v_mfma_f32_32x32x16_bf16 v[32:47], v[70:73], v[90:93], v[32:47]
	ds_read_b64_tr_b16 v[90:91], v161 offset:0x1400
	ds_read_b64_tr_b16 v[92:93], v161 offset:0x1c00
	v_mfma_f32_32x32x16_bf16 v[32:47], v[74:77], v[94:97], v[32:47]
	ds_read_b64_tr_b16 v[94:95], v161 offset:0x2400
	ds_read_b64_tr_b16 v[96:97], v161 offset:0x2c00
	v_mfma_f32_32x32x16_bf16 v[32:47], v[78:81], v[98:101], v[32:47]
	ds_read_b64_tr_b16 v[98:99], v161 offset:0x3400
	ds_read_b64_tr_b16 v[100:101], v161 offset:0x3c00
	s_waitcnt lgkmcnt(0)
	v_mfma_f32_32x32x16_bf16 v[16:31], v[66:69], v[82:85], v[16:31]
	ds_read_b64_tr_b16 v[82:83], v161 offset:0x600
	ds_read_b64_tr_b16 v[84:85], v161 offset:0xe00
	v_mfma_f32_32x32x16_bf16 v[16:31], v[70:73], v[90:93], v[16:31]
	ds_read_b64_tr_b16 v[90:91], v161 offset:0x1600
	ds_read_b64_tr_b16 v[92:93], v161 offset:0x1e00
	v_mfma_f32_32x32x16_bf16 v[16:31], v[74:77], v[94:97], v[16:31]
	ds_read_b64_tr_b16 v[94:95], v161 offset:0x2600
	ds_read_b64_tr_b16 v[96:97], v161 offset:0x2e00
	v_mfma_f32_32x32x16_bf16 v[16:31], v[78:81], v[98:101], v[16:31]
	ds_read_b64_tr_b16 v[98:99], v161 offset:0x3600
	ds_read_b64_tr_b16 v[100:101], v161 offset:0x3e00
	s_waitcnt lgkmcnt(0)
	v_mfma_f32_32x32x16_bf16 v[0:15], v[66:69], v[82:85], v[0:15]
	v_mov_b32_e32 v66, 0xf149f2ca
	v_mov_b32_e32 v67, 0xf149f2ca
	s_nop 1
	v_permlane32_swap_b32_e32 v66, v67
	v_max_f32_e32 v67, v67, v67
	v_max_f32_e32 v66, v66, v66
	v_max_f32_e32 v66, v66, v67
	v_mfma_f32_32x32x16_bf16 v[0:15], v[70:73], v[90:93], v[0:15]
	v_sub_f32_e32 v67, v66, v160
	v_cmp_ge_f32_e32 vcc, s45, v67
	v_max_f32_e32 v67, v160, v160
	v_max_f32_e32 v67, v67, v66
	v_sub_f32_e32 v66, v160, v67
	v_mul_f32_e32 v66, 0x3dd53b94, v66
	v_exp_f32_e32 v66, v66
	v_mfma_f32_32x32x16_bf16 v[0:15], v[74:77], v[94:97], v[0:15]
	s_cmp_eq_u64 vcc, exec
	s_waitcnt vmcnt(0)
	s_cselect_b64 s[38:39], -1, 0
	s_waitcnt lgkmcnt(0)
	s_barrier
; #define RESC(a) do { if (__any((a) < 1.f)) { if (hi == 0) al_l[r32] = (a); asm volatile("s_waitcnt lgkmcnt(0)" ::: "memory"); \
;     for (int d = 0; d < 4; ++d) for (int r = 0; r < 16; ++r) o[d][r] *= al_l[crow(r, hi)]; } } while (0)
; #define WAITV(n) asm volatile("s_waitcnt vmcnt(" #n ")" ::: "memory")
; #define ABAR() do { asm volatile("s_waitcnt lgkmcnt(0)" ::: "memory"); __builtin_amdgcn_s_barrier(); asm volatile("" ::: "memory"); } while (0)
; #define RESC(a) do { if (__any((a) < 1.f)) { if (hi == 0) al_l[r32] = (a); asm volatile("s_waitcnt lgkmcnt(0)" ::: "memory"); \
;     for (int d = 0; d < 4; ++d) for (int r = 0; r < 16; ++r) o[d][r] *= al_l[crow(r, hi)]; } } while (0)
; __device__ __forceinline__ void attn_body2(const bf16_t* __restrict__ Qb, const bf16_t* __restrict__ Kh, const bf16_t* __restrict__ Vh, ...
;     ...
;   pv_d0(o, vb0, pa0, pa1, pa2, pa3); partialSM(pB0, pB1, m_reg, mnB, alB);
;   WAITV(0); ABAR(); RESC(alB);
	v_cndmask_b32_e64 v66, v66, 1.0, s[38:39]
	v_mfma_f32_32x32x16_bf16 v[0:15], v[78:81], v[98:101], v[0:15]
	v_cmp_gt_f32_e32 vcc, 1.0, v66
	s_cbranch_vccz .LBB0_333
	s_and_saveexec_b64 s[2:3], s[36:37]
	s_brev_b32 s31, 1
	s_movk_i32 s52, 0x1f8
	ds_write_b32 v129, v66 offset:128
	s_or_b64 exec, exec, s[2:3]
	s_waitcnt lgkmcnt(0)
	v_add_u32_e32 v80, s87, v128
	ds_read_b128 v[68:71], v80 offset:224
	ds_read_b128 v[72:75], v80 offset:192
	ds_read_b128 v[76:79], v80 offset:160
	ds_read_b128 v[80:83], v80 offset:128
	s_waitcnt lgkmcnt(0)
	v_pk_mul_f32 v[60:61], v[60:61], v[68:69]
	v_pk_mul_f32 v[56:57], v[56:57], v[72:73]
	v_pk_mul_f32 v[52:53], v[52:53], v[76:77]
	v_pk_mul_f32 v[62:63], v[62:63], v[70:71]
	v_pk_mul_f32 v[58:59], v[58:59], v[74:75]
	v_pk_mul_f32 v[54:55], v[54:55], v[78:79]
	v_pk_mul_f32 v[50:51], v[50:51], v[82:83]
	v_pk_mul_f32 v[48:49], v[48:49], v[80:81]
	v_pk_mul_f32 v[44:45], v[44:45], v[68:69]
	v_pk_mul_f32 v[40:41], v[40:41], v[72:73]
	v_pk_mul_f32 v[36:37], v[36:37], v[76:77]
	v_pk_mul_f32 v[46:47], v[46:47], v[70:71]
	v_pk_mul_f32 v[42:43], v[42:43], v[74:75]
	v_pk_mul_f32 v[38:39], v[38:39], v[78:79]
	v_pk_mul_f32 v[34:35], v[34:35], v[82:83]
	v_pk_mul_f32 v[32:33], v[32:33], v[80:81]
	v_pk_mul_f32 v[28:29], v[28:29], v[68:69]
	v_pk_mul_f32 v[24:25], v[24:25], v[72:73]
	v_pk_mul_f32 v[20:21], v[20:21], v[76:77]
	v_pk_mul_f32 v[30:31], v[30:31], v[70:71]
	v_pk_mul_f32 v[26:27], v[26:27], v[74:75]
	v_pk_mul_f32 v[22:23], v[22:23], v[78:79]
	v_pk_mul_f32 v[18:19], v[18:19], v[82:83]
	v_pk_mul_f32 v[16:17], v[16:17], v[80:81]
	v_pk_mul_f32 v[12:13], v[12:13], v[68:69]
	v_pk_mul_f32 v[8:9], v[8:9], v[72:73]
	v_pk_mul_f32 v[4:5], v[4:5], v[76:77]
	v_pk_mul_f32 v[14:15], v[14:15], v[70:71]
	v_pk_mul_f32 v[10:11], v[10:11], v[74:75]
	v_pk_mul_f32 v[6:7], v[6:7], v[78:79]
	v_pk_mul_f32 v[2:3], v[2:3], v[82:83]
	v_pk_mul_f32 v[0:1], v[0:1], v[80:81]
	s_branch .LBB0_334
